# conv item hand-rewritten (weights parked in LDS once per item, all row loads in flight, next-iteration loads issued before the store); hgrn chunk loop-top vmcnt moved to entry edge; v_mov_b64 accumula
# speedup vs baseline: 1.0581x; 1.0304x over previous
.LBB0_93:
	s_add_u32 s0, s0, 0x40080
	s_addc_u32 s1, s1, 0
	s_add_u32 s5, s8, 0x100
	v_mov_b32_e32 v0, 0
	s_addc_u32 s11, s9, 0
	s_mov_b32 s24, -2
	v_mov_b32_e32 v1, 0
	v_mov_b64_e32 v[2:3], 0
	v_mov_b64_e32 v[4:5], 0
	v_mov_b64_e32 v[6:7], 0
	v_mov_b64_e32 v[8:9], 0
	v_mov_b64_e32 v[10:11], 0
	v_mov_b64_e32 v[12:13], 0
	v_mov_b64_e32 v[14:15], 0
	v_mov_b64_e32 v[16:17], 0
	v_mov_b64_e32 v[18:19], 0
	v_mov_b64_e32 v[20:21], 0
	v_mov_b64_e32 v[22:23], 0
	v_mov_b64_e32 v[24:25], 0
	v_mov_b64_e32 v[26:27], 0
	v_mov_b64_e32 v[28:29], 0
	v_mov_b64_e32 v[30:31], 0
	v_mov_b64_e32 v[32:33], 0
	v_mov_b64_e32 v[34:35], 0
	v_mov_b64_e32 v[36:37], 0
	v_mov_b64_e32 v[38:39], 0
	v_mov_b64_e32 v[40:41], 0
	v_mov_b64_e32 v[42:43], 0
	v_mov_b64_e32 v[44:45], 0
	v_mov_b64_e32 v[46:47], 0
	v_mov_b64_e32 v[48:49], 0
	v_mov_b64_e32 v[50:51], 0
	v_mov_b64_e32 v[52:53], 0
	v_mov_b64_e32 v[54:55], 0
	v_mov_b64_e32 v[56:57], 0
	v_mov_b64_e32 v[58:59], 0
	v_mov_b64_e32 v[60:61], 0
	v_mov_b64_e32 v[62:63], 0
	v_mov_b64_e32 v[64:65], 0
	v_mov_b64_e32 v[66:67], 0
	v_mov_b64_e32 v[68:69], 0
	v_mov_b64_e32 v[70:71], 0
	v_mov_b64_e32 v[72:73], 0
	v_mov_b64_e32 v[74:75], 0
	v_mov_b64_e32 v[76:77], 0
	v_mov_b64_e32 v[78:79], 0
	v_mov_b64_e32 v[80:81], 0
	v_mov_b64_e32 v[82:83], 0
	v_mov_b64_e32 v[84:85], 0
	v_mov_b64_e32 v[86:87], 0
	v_mov_b64_e32 v[88:89], 0
	v_mov_b64_e32 v[90:91], 0
	v_mov_b64_e32 v[92:93], 0
	v_mov_b64_e32 v[94:95], 0
	v_mov_b64_e32 v[96:97], 0
	v_mov_b64_e32 v[98:99], 0
	v_mov_b64_e32 v[100:101], 0
	v_mov_b64_e32 v[102:103], 0
	v_mov_b64_e32 v[104:105], 0
	v_mov_b64_e32 v[106:107], 0
	v_mov_b64_e32 v[108:109], 0
	v_mov_b64_e32 v[110:111], 0
	v_mov_b64_e32 v[112:113], 0
	v_mov_b64_e32 v[114:115], 0
	v_mov_b64_e32 v[116:117], 0
	v_mov_b64_e32 v[118:119], 0
	v_mov_b64_e32 v[120:121], 0
	v_mov_b64_e32 v[122:123], 0
	v_mov_b64_e32 v[124:125], 0
	v_mov_b64_e32 v[126:127], 0

.LBB0_405:
	s_add_u32 s20, s20, 0x40080
	s_addc_u32 s21, s21, 0
	s_add_u32 s9, s22, 0x100
	v_mov_b32_e32 v0, 0
	s_addc_u32 s11, s23, 0
	s_mov_b32 s35, -2
	v_mov_b32_e32 v1, 0
	v_mov_b64_e32 v[2:3], 0
	v_mov_b64_e32 v[4:5], 0
	v_mov_b64_e32 v[6:7], 0
	v_mov_b64_e32 v[8:9], 0
	v_mov_b64_e32 v[10:11], 0
	v_mov_b64_e32 v[12:13], 0
	v_mov_b64_e32 v[14:15], 0
	v_mov_b64_e32 v[16:17], 0
	v_mov_b64_e32 v[18:19], 0
	v_mov_b64_e32 v[20:21], 0
	v_mov_b64_e32 v[22:23], 0
	v_mov_b64_e32 v[24:25], 0
	v_mov_b64_e32 v[26:27], 0
	v_mov_b64_e32 v[28:29], 0
	v_mov_b64_e32 v[30:31], 0
	v_mov_b64_e32 v[32:33], 0
	v_mov_b64_e32 v[34:35], 0
	v_mov_b64_e32 v[36:37], 0
	v_mov_b64_e32 v[38:39], 0
	v_mov_b64_e32 v[40:41], 0
	v_mov_b64_e32 v[42:43], 0
	v_mov_b64_e32 v[44:45], 0
	v_mov_b64_e32 v[46:47], 0
	v_mov_b64_e32 v[48:49], 0
	v_mov_b64_e32 v[50:51], 0
	v_mov_b64_e32 v[52:53], 0
	v_mov_b64_e32 v[54:55], 0
	v_mov_b64_e32 v[56:57], 0
	v_mov_b64_e32 v[58:59], 0
	v_mov_b64_e32 v[60:61], 0
	v_mov_b64_e32 v[62:63], 0
	v_mov_b64_e32 v[64:65], 0
	v_mov_b64_e32 v[66:67], 0
	v_mov_b64_e32 v[68:69], 0
	v_mov_b64_e32 v[70:71], 0
	v_mov_b64_e32 v[72:73], 0
	v_mov_b64_e32 v[74:75], 0
	v_mov_b64_e32 v[76:77], 0
	v_mov_b64_e32 v[78:79], 0
	v_mov_b64_e32 v[80:81], 0
	v_mov_b64_e32 v[82:83], 0
	v_mov_b64_e32 v[84:85], 0
	v_mov_b64_e32 v[86:87], 0
	v_mov_b64_e32 v[88:89], 0
	v_mov_b64_e32 v[90:91], 0
	v_mov_b64_e32 v[92:93], 0
	v_mov_b64_e32 v[94:95], 0
	v_mov_b64_e32 v[96:97], 0
	v_mov_b64_e32 v[98:99], 0
	v_mov_b64_e32 v[100:101], 0
	v_mov_b64_e32 v[102:103], 0
	v_mov_b64_e32 v[104:105], 0
	v_mov_b64_e32 v[106:107], 0
	v_mov_b64_e32 v[108:109], 0
	v_mov_b64_e32 v[110:111], 0
	v_mov_b64_e32 v[112:113], 0
	v_mov_b64_e32 v[114:115], 0
	v_mov_b64_e32 v[116:117], 0
	v_mov_b64_e32 v[118:119], 0
	v_mov_b64_e32 v[120:121], 0
	v_mov_b64_e32 v[122:123], 0
	v_mov_b64_e32 v[124:125], 0
	v_mov_b64_e32 v[126:127], 0
	s_mov_b32 s39, 0x10000

.LBB0_441:
	s_ashr_i32 s21, s20, 31
	s_lshl_b64 s[24:25], s[20:21], 8
	s_add_i32 s3, s2, -2
	v_mul_lo_u32 v0, s20, v199
	s_add_u32 s10, s10, 0x80
	v_add_lshl_u32 v200, v0, v218, 1
	v_mul_lo_u32 v0, s20, v219
	s_addc_u32 s11, s11, 0
	v_add_lshl_u32 v202, v0, v220, 1
	v_mov_b32_e32 v129, v191
	s_add_u32 s26, s26, 0x100
	v_mov_b32_e32 v0, 0
	v_mov_b32_e32 v201, v191
	v_mov_b32_e32 v203, v191
	s_addc_u32 s27, s27, 0
	v_lshl_add_u64 v[130:131], s[8:9], 0, v[190:191]
	v_lshl_add_u64 v[132:133], s[8:9], 0, v[128:129]
	s_mov_b32 s21, 0
	v_mov_b32_e32 v1, 0
	v_mov_b64_e32 v[2:3], 0
	v_mov_b64_e32 v[4:5], 0
	v_mov_b64_e32 v[6:7], 0
	v_mov_b64_e32 v[8:9], 0
	v_mov_b64_e32 v[10:11], 0
	v_mov_b64_e32 v[12:13], 0
	v_mov_b64_e32 v[14:15], 0
	v_mov_b64_e32 v[16:17], 0
	v_mov_b64_e32 v[18:19], 0
	v_mov_b64_e32 v[20:21], 0
	v_mov_b64_e32 v[22:23], 0
	v_mov_b64_e32 v[24:25], 0
	v_mov_b64_e32 v[26:27], 0
	v_mov_b64_e32 v[28:29], 0
	v_mov_b64_e32 v[30:31], 0
	v_mov_b64_e32 v[32:33], 0
	v_mov_b64_e32 v[34:35], 0
	v_mov_b64_e32 v[36:37], 0
	v_mov_b64_e32 v[38:39], 0
	v_mov_b64_e32 v[40:41], 0
	v_mov_b64_e32 v[42:43], 0
	v_mov_b64_e32 v[44:45], 0
	v_mov_b64_e32 v[46:47], 0
	v_mov_b64_e32 v[48:49], 0
	v_mov_b64_e32 v[50:51], 0
	v_mov_b64_e32 v[52:53], 0
	v_mov_b64_e32 v[54:55], 0
	v_mov_b64_e32 v[56:57], 0
	v_mov_b64_e32 v[58:59], 0
	v_mov_b64_e32 v[60:61], 0
	v_mov_b64_e32 v[62:63], 0
	v_mov_b64_e32 v[64:65], 0
	v_mov_b64_e32 v[66:67], 0
	v_mov_b64_e32 v[68:69], 0
	v_mov_b64_e32 v[70:71], 0
	v_mov_b64_e32 v[72:73], 0
	v_mov_b64_e32 v[74:75], 0
	v_mov_b64_e32 v[76:77], 0
	v_mov_b64_e32 v[78:79], 0
	v_mov_b64_e32 v[80:81], 0
	v_mov_b64_e32 v[82:83], 0
	v_mov_b64_e32 v[84:85], 0
	v_mov_b64_e32 v[86:87], 0
	v_mov_b64_e32 v[88:89], 0
	v_mov_b64_e32 v[90:91], 0
	v_mov_b64_e32 v[92:93], 0
	v_mov_b64_e32 v[94:95], 0
	v_mov_b64_e32 v[96:97], 0
	v_mov_b64_e32 v[98:99], 0
	v_mov_b64_e32 v[100:101], 0
	v_mov_b64_e32 v[102:103], 0
	v_mov_b64_e32 v[104:105], 0
	v_mov_b64_e32 v[106:107], 0
	v_mov_b64_e32 v[108:109], 0
	v_mov_b64_e32 v[110:111], 0
	v_mov_b64_e32 v[112:113], 0
	v_mov_b64_e32 v[114:115], 0
	v_mov_b64_e32 v[116:117], 0
	v_mov_b64_e32 v[118:119], 0
	v_mov_b64_e32 v[120:121], 0
	v_mov_b64_e32 v[122:123], 0
	v_mov_b64_e32 v[124:125], 0
	v_mov_b64_e32 v[126:127], 0
	s_branch .LBB0_443

.LBB0_487:
	v_readlane_b32 s28, v246, 25
	v_readlane_b32 s29, v246, 26
	v_readlane_b32 s26, v246, 16
	v_readlane_b32 s4, v248, 59
	v_readlane_b32 s5, v248, 60
	v_readlane_b32 s6, v248, 63
	v_readlane_b32 s7, v247, 0
	v_readlane_b32 s8, v248, 24
	v_readlane_b32 s9, v248, 25
	v_and_b32_e32 v249, 63, v188
	v_lshlrev_b32_e32 v251, 5, v249
	v_lshlrev_b32_e32 v249, 4, v249
	v_lshlrev_b32_e32 v250, 4, v188
	v_readfirstlane_b32 s10, v210
	s_add_u32 s12, s28, 0x1000
	s_addc_u32 s13, s29, 0
	global_load_dwordx4 v[0:3], v251, s[28:29]
	global_load_dwordx4 v[4:7], v251, s[28:29] offset:16
	global_load_dwordx4 v[8:11], v251, s[28:29] offset:2048
	global_load_dwordx4 v[12:15], v251, s[28:29] offset:2064
	global_load_dwordx4 v[16:19], v251, s[12:13]
	global_load_dwordx4 v[20:23], v251, s[12:13] offset:16
	s_lshl_b32 s11, s46, 7
	s_add_i32 s10, s10, s11
	s_mov_b32 s11, 0
	s_cmp_gt_u32 s10, 0xffff
	s_cselect_b32 s13, 1, 0
	s_waitcnt vmcnt(0)
	ds_write_b128 v250, v[0:3]
	ds_write_b128 v250, v[4:7] offset:8192
	ds_write_b128 v250, v[8:11] offset:16384
	ds_write_b128 v250, v[12:15] offset:24576
	ds_write_b128 v250, v[16:19] offset:32768
	ds_write_b128 v250, v[20:23] offset:40960
	s_waitcnt lgkmcnt(0)
.Lcv_top:
	s_and_b32 s12, s10, 0x7ff
	s_cmp_lg_u32 s13, 0
	s_cbranch_scc0 .Lcv_tp0
	s_and_b32 s12, s10, 15
.Lcv_tp0:
	s_add_i32 s14, s10, -2
	s_ashr_i32 s15, s14, 31
	s_lshl_b64 s[14:15], s[14:15], 10
	s_add_u32 s0, s4, s14
	s_addc_u32 s1, s5, s15
	s_lshl_b32 s14, s10, 10
	s_add_u32 s2, s6, s14
	s_addc_u32 s3, s7, 0
	s_cmp_lt_u32 s12, 2
	s_cbranch_scc1 .Lcv_slow
	global_load_dwordx4 v[0:3], v249, s[0:1]
	global_load_dwordx4 v[4:7], v249, s[0:1] offset:1024
	global_load_dwordx4 v[8:11], v249, s[0:1] offset:2048
	global_load_dwordx4 v[12:15], v249, s[2:3]
	s_waitcnt vmcnt(0)
.Lcv_fast:
	ds_read_b128 v[16:19], v250
	ds_read_b128 v[20:23], v250 offset:8192
	ds_read_b128 v[24:27], v250 offset:16384
	ds_read_b128 v[28:31], v250 offset:24576
	s_waitcnt vmcnt(4)
	v_lshlrev_b32_e32 v32, 16, v0
	v_lshlrev_b32_e32 v33, 16, v1
	v_lshlrev_b32_e32 v34, 16, v2
	v_lshlrev_b32_e32 v190, 16, v3
	v_and_b32_e32 v0, 0xffff0000, v0
	v_and_b32_e32 v1, 0xffff0000, v1
	v_and_b32_e32 v2, 0xffff0000, v2
	v_and_b32_e32 v3, 0xffff0000, v3
	s_waitcnt lgkmcnt(2)
	v_fma_f32 v16, v32, v16, 0
	v_fma_f32 v17, v0, v17, 0
	v_fma_f32 v18, v33, v18, 0
	v_fma_f32 v19, v1, v19, 0
	v_fma_f32 v20, v34, v20, 0
	v_fma_f32 v21, v2, v21, 0
	v_fma_f32 v22, v190, v22, 0
	v_fma_f32 v23, v3, v23, 0
	s_waitcnt vmcnt(3)
	v_lshlrev_b32_e32 v32, 16, v4
	v_lshlrev_b32_e32 v33, 16, v5
	v_lshlrev_b32_e32 v34, 16, v6
	v_lshlrev_b32_e32 v190, 16, v7
	v_and_b32_e32 v4, 0xffff0000, v4
	v_and_b32_e32 v5, 0xffff0000, v5
	v_and_b32_e32 v6, 0xffff0000, v6
	v_and_b32_e32 v7, 0xffff0000, v7
	s_waitcnt lgkmcnt(0)
	v_fmac_f32_e32 v16, v32, v24
	v_fmac_f32_e32 v17, v4, v25
	v_fmac_f32_e32 v18, v33, v26
	v_fmac_f32_e32 v19, v5, v27
	v_fmac_f32_e32 v20, v34, v28
	v_fmac_f32_e32 v21, v6, v29
	v_fmac_f32_e32 v22, v190, v30
	v_fmac_f32_e32 v23, v7, v31
	ds_read_b128 v[24:27], v250 offset:32768
	ds_read_b128 v[28:31], v250 offset:40960
	s_waitcnt vmcnt(2)
	v_lshlrev_b32_e32 v32, 16, v8
	v_lshlrev_b32_e32 v33, 16, v9
	v_lshlrev_b32_e32 v34, 16, v10
	v_lshlrev_b32_e32 v190, 16, v11
	v_and_b32_e32 v8, 0xffff0000, v8
	v_and_b32_e32 v9, 0xffff0000, v9
	v_and_b32_e32 v10, 0xffff0000, v10
	v_and_b32_e32 v11, 0xffff0000, v11
	s_waitcnt lgkmcnt(0)
	v_fmac_f32_e32 v16, v32, v24
	v_fmac_f32_e32 v17, v8, v25
	v_fmac_f32_e32 v18, v33, v26
	v_fmac_f32_e32 v19, v9, v27
	v_fmac_f32_e32 v20, v34, v28
	v_fmac_f32_e32 v21, v10, v29
	v_fmac_f32_e32 v22, v190, v30
	v_fmac_f32_e32 v23, v11, v31
	s_waitcnt vmcnt(1)
	v_lshlrev_b32_e32 v32, 16, v12
	v_lshlrev_b32_e32 v33, 16, v13
	v_lshlrev_b32_e32 v34, 16, v14
	v_lshlrev_b32_e32 v190, 16, v15
	v_and_b32_e32 v12, 0xffff0000, v12
	v_and_b32_e32 v13, 0xffff0000, v13
	v_and_b32_e32 v14, 0xffff0000, v14
	v_and_b32_e32 v15, 0xffff0000, v15
	v_mul_f32_e32 v32, v16, v32
	v_mul_f32_e32 v12, v17, v12
	v_mul_f32_e32 v33, v18, v33
	v_mul_f32_e32 v13, v19, v13
	v_mul_f32_e32 v34, v20, v34
	v_mul_f32_e32 v14, v21, v14
	v_mul_f32_e32 v190, v22, v190
	v_mul_f32_e32 v15, v23, v15
	v_cvt_pk_bf16_f32 v16, v32, v12
	v_cvt_pk_bf16_f32 v17, v33, v13
	v_cvt_pk_bf16_f32 v18, v34, v14
	v_cvt_pk_bf16_f32 v19, v190, v15
	s_mov_b64 s[16:17], s[2:3]
	s_add_i32 s11, s11, 1
	s_cmp_eq_u32 s11, 16
	s_cbranch_scc1 .Lcv_last
	s_add_i32 s10, s10, 8
	s_and_b32 s12, s10, 0x7ff
	s_cmp_lg_u32 s13, 0
	s_cbranch_scc0 .Lcv_tp1
	s_and_b32 s12, s10, 15
.Lcv_tp1:
	s_add_i32 s14, s10, -2
	s_ashr_i32 s15, s14, 31
	s_lshl_b64 s[14:15], s[14:15], 10
	s_add_u32 s0, s4, s14
	s_addc_u32 s1, s5, s15
	s_lshl_b32 s14, s10, 10
	s_add_u32 s2, s6, s14
	s_addc_u32 s3, s7, 0
	s_cmp_lt_u32 s12, 2
	s_cbranch_scc1 .Lcv_st_top
	global_load_dwordx4 v[0:3], v249, s[0:1]
	global_load_dwordx4 v[4:7], v249, s[0:1] offset:1024
	global_load_dwordx4 v[8:11], v249, s[0:1] offset:2048
	global_load_dwordx4 v[12:15], v249, s[2:3]
	global_store_dwordx4 v249, v[16:19], s[16:17]
	s_nop 1
	s_branch .Lcv_fast
.Lcv_st_top:
	global_store_dwordx4 v249, v[16:19], s[16:17]
	s_nop 1
	s_branch .Lcv_top
.Lcv_last:
	global_store_dwordx4 v249, v[16:19], s[16:17]
	s_branch .Lcv_done
.Lcv_slow:
	v_mov_b32_e32 v16, 0
	v_mov_b32_e32 v17, 0
	v_mov_b32_e32 v18, 0
	v_mov_b32_e32 v19, 0
	v_mov_b32_e32 v20, 0
	v_mov_b32_e32 v21, 0
	v_mov_b32_e32 v22, 0
	v_mov_b32_e32 v23, 0
	s_add_i32 s18, s10, 0xffff0000
	s_lshr_b32 s18, s18, 4
	s_add_i32 s18, s18, s26
	s_lshl_b32 s18, s18, 12
	s_add_u32 s20, s8, s18
	s_addc_u32 s21, s9, 0
	s_add_i32 s18, s12, 0
	s_cmp_lt_u32 s18, 2
	s_cbranch_scc1 .Lcv_sp0
	global_load_dwordx4 v[0:3], v249, s[0:1]
	ds_read_b128 v[24:27], v250
	ds_read_b128 v[28:31], v250 offset:8192
	s_waitcnt vmcnt(0) lgkmcnt(0)
	v_lshlrev_b32_e32 v32, 16, v0
	v_lshlrev_b32_e32 v33, 16, v1
	v_lshlrev_b32_e32 v34, 16, v2
	v_lshlrev_b32_e32 v190, 16, v3
	v_and_b32_e32 v0, 0xffff0000, v0
	v_and_b32_e32 v1, 0xffff0000, v1
	v_and_b32_e32 v2, 0xffff0000, v2
	v_and_b32_e32 v3, 0xffff0000, v3
	v_fmac_f32_e32 v16, v32, v24
	v_fmac_f32_e32 v17, v0, v25
	v_fmac_f32_e32 v18, v33, v26
	v_fmac_f32_e32 v19, v1, v27
	v_fmac_f32_e32 v20, v34, v28
	v_fmac_f32_e32 v21, v2, v29
	v_fmac_f32_e32 v22, v190, v30
	v_fmac_f32_e32 v23, v3, v31
	s_branch .Lcv_sd0
.Lcv_sp0:
	s_cmp_lg_u32 s13, 0
	s_cbranch_scc0 .Lcv_sd0
	s_lshl_b32 s22, s18, 11
	s_add_u32 s22, s20, s22
	s_addc_u32 s23, s21, 0
	global_load_dwordx4 v[0:3], v251, s[22:23]
	global_load_dwordx4 v[4:7], v251, s[22:23] offset:16
	ds_read_b128 v[24:27], v250
	ds_read_b128 v[28:31], v250 offset:8192
	s_waitcnt vmcnt(0) lgkmcnt(0)
	v_fmac_f32_e32 v16, v0, v24
	v_fmac_f32_e32 v17, v1, v25
	v_fmac_f32_e32 v18, v2, v26
	v_fmac_f32_e32 v19, v3, v27
	v_fmac_f32_e32 v20, v4, v28
	v_fmac_f32_e32 v21, v5, v29
	v_fmac_f32_e32 v22, v6, v30
	v_fmac_f32_e32 v23, v7, v31
.Lcv_sd0:
	s_add_i32 s18, s12, 1
	s_cmp_lt_u32 s18, 2
	s_cbranch_scc1 .Lcv_sp1
	global_load_dwordx4 v[0:3], v249, s[0:1] offset:1024
	ds_read_b128 v[24:27], v250 offset:16384
	ds_read_b128 v[28:31], v250 offset:24576
	s_waitcnt vmcnt(0) lgkmcnt(0)
	v_lshlrev_b32_e32 v32, 16, v0
	v_lshlrev_b32_e32 v33, 16, v1
	v_lshlrev_b32_e32 v34, 16, v2
	v_lshlrev_b32_e32 v190, 16, v3
	v_and_b32_e32 v0, 0xffff0000, v0
	v_and_b32_e32 v1, 0xffff0000, v1
	v_and_b32_e32 v2, 0xffff0000, v2
	v_and_b32_e32 v3, 0xffff0000, v3
	v_fmac_f32_e32 v16, v32, v24
	v_fmac_f32_e32 v17, v0, v25
	v_fmac_f32_e32 v18, v33, v26
	v_fmac_f32_e32 v19, v1, v27
	v_fmac_f32_e32 v20, v34, v28
	v_fmac_f32_e32 v21, v2, v29
	v_fmac_f32_e32 v22, v190, v30
	v_fmac_f32_e32 v23, v3, v31
	s_branch .Lcv_sd1
.Lcv_sp1:
	s_cmp_lg_u32 s13, 0
	s_cbranch_scc0 .Lcv_sd1
	s_lshl_b32 s22, s18, 11
	s_add_u32 s22, s20, s22
	s_addc_u32 s23, s21, 0
	global_load_dwordx4 v[0:3], v251, s[22:23]
	global_load_dwordx4 v[4:7], v251, s[22:23] offset:16
	ds_read_b128 v[24:27], v250 offset:16384
	ds_read_b128 v[28:31], v250 offset:24576
	s_waitcnt vmcnt(0) lgkmcnt(0)
	v_fmac_f32_e32 v16, v0, v24
	v_fmac_f32_e32 v17, v1, v25
	v_fmac_f32_e32 v18, v2, v26
	v_fmac_f32_e32 v19, v3, v27
	v_fmac_f32_e32 v20, v4, v28
	v_fmac_f32_e32 v21, v5, v29
	v_fmac_f32_e32 v22, v6, v30
	v_fmac_f32_e32 v23, v7, v31
.Lcv_sd1:
	s_add_i32 s18, s12, 2
	s_cmp_lt_u32 s18, 2
	s_cbranch_scc1 .Lcv_sp2
	global_load_dwordx4 v[0:3], v249, s[0:1] offset:2048
	ds_read_b128 v[24:27], v250 offset:32768
	ds_read_b128 v[28:31], v250 offset:40960
	s_waitcnt vmcnt(0) lgkmcnt(0)
	v_lshlrev_b32_e32 v32, 16, v0
	v_lshlrev_b32_e32 v33, 16, v1
	v_lshlrev_b32_e32 v34, 16, v2
	v_lshlrev_b32_e32 v190, 16, v3
	v_and_b32_e32 v0, 0xffff0000, v0
	v_and_b32_e32 v1, 0xffff0000, v1
	v_and_b32_e32 v2, 0xffff0000, v2
	v_and_b32_e32 v3, 0xffff0000, v3
	v_fmac_f32_e32 v16, v32, v24
	v_fmac_f32_e32 v17, v0, v25
	v_fmac_f32_e32 v18, v33, v26
	v_fmac_f32_e32 v19, v1, v27
	v_fmac_f32_e32 v20, v34, v28
	v_fmac_f32_e32 v21, v2, v29
	v_fmac_f32_e32 v22, v190, v30
	v_fmac_f32_e32 v23, v3, v31
	s_branch .Lcv_sd2
.Lcv_sp2:
.Lcv_sd2:
	global_load_dwordx4 v[12:15], v249, s[2:3]
	s_waitcnt vmcnt(0)
	v_lshlrev_b32_e32 v32, 16, v12
	v_lshlrev_b32_e32 v33, 16, v13
	v_lshlrev_b32_e32 v34, 16, v14
	v_lshlrev_b32_e32 v190, 16, v15
	v_and_b32_e32 v12, 0xffff0000, v12
	v_and_b32_e32 v13, 0xffff0000, v13
	v_and_b32_e32 v14, 0xffff0000, v14
	v_and_b32_e32 v15, 0xffff0000, v15
	v_mul_f32_e32 v32, v16, v32
	v_mul_f32_e32 v12, v17, v12
	v_mul_f32_e32 v33, v18, v33
	v_mul_f32_e32 v13, v19, v13
	v_mul_f32_e32 v34, v20, v34
	v_mul_f32_e32 v14, v21, v14
	v_mul_f32_e32 v190, v22, v190
	v_mul_f32_e32 v15, v23, v15
	v_cvt_pk_bf16_f32 v16, v32, v12
	v_cvt_pk_bf16_f32 v17, v33, v13
	v_cvt_pk_bf16_f32 v18, v34, v14
	v_cvt_pk_bf16_f32 v19, v190, v15
	global_store_dwordx4 v249, v[16:19], s[2:3]
	s_nop 1
	s_add_i32 s11, s11, 1
	s_add_i32 s10, s10, 8
	s_cmp_lt_u32 s11, 16
	s_cbranch_scc1 .Lcv_top
.Lcv_done:
.LBB0_502:
	s_mov_b64 s[0:1], 0

.LBB0_800:
	s_ashr_i32 s0, s2, 2
	s_ashr_i32 s3, s2, 7
	s_and_b32 s10, s0, 0xffffffc0
	s_add_i32 s85, s86, -1
	s_lshl_b32 s0, s3, 4
	s_min_i32 s1, s0, s85
	s_add_i32 s4, s1, s91
	v_and_b32_e32 v117, 0x7f, v94
	s_ashr_i32 s5, s4, 31
	s_mov_b32 s54, 1
	s_mov_b32 s1, s0
	v_lshl_or_b32 v74, s84, 7, v117
	s_lshl_b64 s[4:5], s[4:5], 9
	s_or_b64 s[62:63], s[0:1], s[54:55]
	v_or_b32_e32 v0, s4, v74
	s_min_i32 s4, s62, s85
	s_add_i32 s4, s4, s91
	v_mov_b32_e32 v1, s5
	s_ashr_i32 s5, s4, 31
	s_lshl_b64 s[4:5], s[4:5], 9
	s_or_b32 s81, s0, 2
	v_or_b32_e32 v2, s4, v74
	s_min_i32 s4, s81, s85
	s_add_i32 s4, s4, s91
	v_mov_b32_e32 v3, s5
	s_ashr_i32 s5, s4, 31
	s_lshl_b64 s[4:5], s[4:5], 9
	v_or_b32_e32 v4, s4, v74
	s_min_i32 s4, s63, s85
	s_add_i32 s4, s4, s91
	v_mov_b32_e32 v5, s5
	s_ashr_i32 s5, s4, 31
	s_lshl_b64 s[4:5], s[4:5], 9
	v_or_b32_e32 v6, s4, v74
	v_mov_b32_e32 v7, s5
	s_mov_b32 s4, 4
	s_mov_b32 s5, 6
	s_or_b64 s[64:65], s[0:1], s[4:5]
	s_min_i32 s4, s64, s85
	s_add_i32 s4, s4, s91
	s_ashr_i32 s5, s4, 31
	s_lshl_b64 s[4:5], s[4:5], 9
	v_or_b32_e32 v20, s4, v74
	v_mov_b32_e32 v21, s5
	s_mov_b32 s4, 5
	s_mov_b32 s5, 7
	s_or_b64 s[66:67], s[0:1], s[4:5]
	s_min_i32 s4, s66, s85
	s_add_i32 s4, s4, s91
	s_ashr_i32 s5, s4, 31
	s_lshl_b64 s[4:5], s[4:5], 9
	v_or_b32_e32 v36, s4, v74
	s_min_i32 s4, s65, s85
	s_add_i32 s4, s4, s91
	v_mov_b32_e32 v37, s5
	s_ashr_i32 s5, s4, 31
	s_lshl_b64 s[4:5], s[4:5], 9
	v_or_b32_e32 v46, s4, v74
	s_min_i32 s4, s67, s85
	s_add_i32 s4, s4, s91
	v_mov_b32_e32 v47, s5
	s_ashr_i32 s5, s4, 31
	s_lshl_b64 s[4:5], s[4:5], 9
	v_or_b32_e32 v48, s4, v74
	v_mov_b32_e32 v49, s5
	s_mov_b32 s4, 8
	s_mov_b32 s5, 10
	s_or_b64 s[68:69], s[0:1], s[4:5]
	s_min_i32 s4, s68, s85
	s_add_i32 s4, s4, s91
	s_ashr_i32 s5, s4, 31
	s_lshl_b64 s[4:5], s[4:5], 9
	v_or_b32_e32 v50, s4, v74
	v_mov_b32_e32 v51, s5
	s_mov_b32 s4, 9
	s_mov_b32 s5, 11
	s_or_b64 s[70:71], s[0:1], s[4:5]
	s_min_i32 s4, s70, s85
	s_add_i32 s4, s4, s91
	s_ashr_i32 s5, s4, 31
	s_lshl_b64 s[4:5], s[4:5], 9
	v_or_b32_e32 v52, s4, v74
	s_min_i32 s4, s69, s85
	s_add_i32 s4, s4, s91
	v_mov_b32_e32 v53, s5
	s_ashr_i32 s5, s4, 31
	s_lshl_b64 s[4:5], s[4:5], 9
	v_or_b32_e32 v54, s4, v74
	s_min_i32 s4, s71, s85
	s_add_i32 s4, s4, s91
	v_mov_b32_e32 v55, s5
	s_ashr_i32 s5, s4, 31
	s_lshl_b64 s[4:5], s[4:5], 9
	v_or_b32_e32 v56, s4, v74
	v_mov_b32_e32 v57, s5
	s_mov_b32 s4, 12
	s_mov_b32 s5, 14
	s_or_b64 s[72:73], s[0:1], s[4:5]
	s_min_i32 s4, s72, s85
	s_add_i32 s4, s4, s91
	s_ashr_i32 s5, s4, 31
	s_lshl_b64 s[4:5], s[4:5], 9
	v_or_b32_e32 v58, s4, v74
	v_mov_b32_e32 v59, s5
	s_mov_b32 s4, 13
	s_mov_b32 s5, 15
	s_or_b64 s[74:75], s[0:1], s[4:5]
	s_min_i32 s1, s74, s85
	s_add_i32 s4, s1, s91
	s_ashr_i32 s5, s4, 31
	s_lshl_b64 s[4:5], s[4:5], 9
	s_min_i32 s1, s73, s85
	v_or_b32_e32 v82, s4, v74
	s_add_i32 s4, s1, s91
	v_mov_b32_e32 v83, s5
	s_ashr_i32 s5, s4, 31
	s_lshl_b64 s[4:5], s[4:5], 9
	s_min_i32 s1, s75, s85
	v_or_b32_e32 v84, s4, v74
	s_add_i32 s4, s1, s91
	v_mov_b32_e32 v85, s5
	s_ashr_i32 s5, s4, 31
	v_readlane_b32 s16, v248, 49
	s_lshl_b64 s[4:5], s[4:5], 9
	s_lshl_b32 s14, s84, 8
	v_readlane_b32 s28, v248, 61
	v_or_b32_e32 v86, s4, v74
	v_readlane_b32 s29, v248, 62
	s_add_u32 s4, s28, s14
	v_mov_b32_e32 v87, s5
	v_readlane_b32 s19, v248, 52
	s_addc_u32 s5, s29, 0
	s_and_b32 s1, s2, 0x3fffff80
	s_lshl_b32 s1, s1, 2
	v_readlane_b32 s19, v247, 36
	s_add_i32 s16, s19, s1
	v_lshlrev_b32_e32 v22, 3, v94
	s_cmpk_lt_u32 s2, 0x80
	v_and_b32_e32 v119, 0x78, v22
	s_cselect_b64 s[76:77], -1, 0
	s_cmp_eq_u32 s3, 1
	v_readlane_b32 s17, v248, 50
	v_readlane_b32 s20, v248, 53
	v_readlane_b32 s21, v248, 54
	v_lshlrev_b32_e32 v190, 1, v119
	s_cselect_b64 s[6:7], -1, 0
	s_lshl_b32 s1, s3, 5
	v_readlane_b32 s18, v248, 51
	v_lshl_add_u64 v[76:77], s[4:5], 0, v[190:191]
	s_add_i32 s17, s1, 0x100
	s_bfe_u32 s4, s2, 0x20006
	s_and_b32 s5, s2, 0xffffffc0
	s_lshl_b32 s1, s12, 5
	v_readlane_b32 s21, v247, 38
	v_readlane_b32 s20, v247, 37
	s_lshl_b32 s13, s4, 4
	s_ashr_i32 s11, s10, 31
	s_add_i32 s18, s21, s1
	s_add_i32 s1, s20, s5
	s_cmp_eq_u32 s3, 2
	s_cselect_b64 s[8:9], -1, 0
	v_writelane_b32 v246, s8, 38
	v_or_b32_e32 v22, s10, v61
	v_readlane_b32 s36, v247, 7
	v_writelane_b32 v246, s9, 39
	v_ashrrev_i32_e32 v23, 31, v22
	v_readlane_b32 s8, v246, 27
	v_readlane_b32 s9, v246, 28
	v_readlane_b32 s37, v247, 8
	v_readlane_b32 s44, v247, 15
	v_readlane_b32 s45, v247, 16
	v_lshl_add_u64 v[88:89], v[22:23], 2, s[8:9]
	global_load_dword v69, v[88:89], off
	global_load_dword v71, v[88:89], off offset:64
	global_load_dword v73, v[88:89], off offset:128
	global_load_dword v75, v[88:89], off offset:192
	v_lshl_add_u64 v[88:89], v[0:1], 2, s[44:45]
	v_lshl_add_u64 v[0:1], v[0:1], 1, s[36:37]
	global_load_dword v88, v[88:89], off
	v_readlane_b32 s22, v248, 55
	global_load_ushort v89, v[0:1], off
	v_lshl_add_u64 v[0:1], v[2:3], 2, s[44:45]
	global_load_dword v90, v[0:1], off
	v_lshl_add_u64 v[0:1], v[2:3], 1, s[36:37]
	global_load_ushort v91, v[0:1], off
	v_lshl_add_u64 v[0:1], v[4:5], 2, s[44:45]
	global_load_dword v92, v[0:1], off
	v_lshl_add_u64 v[0:1], v[4:5], 1, s[36:37]
	global_load_ushort v93, v[0:1], off
	v_lshl_add_u64 v[0:1], v[6:7], 2, s[44:45]
	global_load_dword v98, v[0:1], off
	v_lshl_add_u64 v[0:1], v[6:7], 1, s[36:37]
	global_load_ushort v100, v[0:1], off
	v_lshl_add_u64 v[0:1], v[20:21], 2, s[44:45]
	global_load_dword v102, v[0:1], off
	v_lshl_add_u64 v[0:1], v[20:21], 1, s[36:37]
	global_load_ushort v103, v[0:1], off
	v_lshl_add_u64 v[0:1], v[36:37], 2, s[44:45]
	global_load_dword v104, v[0:1], off
	v_lshl_add_u64 v[0:1], v[36:37], 1, s[36:37]
	global_load_ushort v105, v[0:1], off
	v_lshl_add_u64 v[0:1], v[46:47], 2, s[44:45]
	global_load_dword v106, v[0:1], off
	v_lshl_add_u64 v[0:1], v[46:47], 1, s[36:37]
	global_load_ushort v107, v[0:1], off
	v_lshl_add_u64 v[0:1], v[48:49], 2, s[44:45]
	global_load_dword v108, v[0:1], off
	v_lshl_add_u64 v[0:1], v[48:49], 1, s[36:37]
	global_load_ushort v109, v[0:1], off
	v_lshl_add_u64 v[0:1], v[50:51], 2, s[44:45]
	global_load_dword v110, v[0:1], off
	v_lshl_add_u64 v[0:1], v[50:51], 1, s[36:37]
	global_load_ushort v111, v[0:1], off
	v_lshl_add_u64 v[0:1], v[52:53], 2, s[44:45]
	global_load_dword v112, v[0:1], off
	v_lshl_add_u64 v[0:1], v[52:53], 1, s[36:37]
	global_load_ushort v113, v[0:1], off
	v_lshl_add_u64 v[0:1], v[54:55], 2, s[44:45]
	global_load_dword v114, v[0:1], off
	v_lshl_add_u64 v[0:1], v[54:55], 1, s[36:37]
	global_load_ushort v115, v[0:1], off
	v_lshl_add_u64 v[0:1], v[56:57], 2, s[44:45]
	global_load_dword v116, v[0:1], off
	v_lshl_add_u64 v[0:1], v[56:57], 1, s[36:37]
	global_load_ushort v118, v[0:1], off
	v_lshl_add_u64 v[0:1], v[58:59], 2, s[44:45]
	global_load_dword v133, v[0:1], off
	v_lshl_add_u64 v[0:1], v[58:59], 1, s[36:37]
	global_load_ushort v138, v[0:1], off
	v_lshl_add_u64 v[0:1], v[82:83], 2, s[44:45]
	global_load_dword v139, v[0:1], off
	v_lshl_add_u64 v[0:1], v[82:83], 1, s[36:37]
	global_load_ushort v140, v[0:1], off
	v_lshl_add_u64 v[0:1], v[84:85], 2, s[44:45]
	global_load_dword v141, v[0:1], off
	v_lshl_add_u64 v[0:1], v[84:85], 1, s[36:37]
	global_load_ushort v142, v[0:1], off
	v_lshl_add_u64 v[0:1], v[86:87], 2, s[44:45]
	v_add_u32_e32 v2, 0x200, v94
	global_load_dword v143, v[0:1], off
	v_lshl_add_u64 v[0:1], v[86:87], 1, s[36:37]
	v_ashrrev_i32_e32 v86, 4, v94
	v_ashrrev_i32_e32 v87, 4, v2
	global_load_ushort v144, v[0:1], off
	v_min_i32_e32 v0, s85, v86
	v_min_i32_e32 v2, s85, v87
	v_add_u32_e32 v0, s91, v0
	v_add_u32_e32 v2, s91, v2
	v_ashrrev_i32_e32 v1, 31, v0
	v_ashrrev_i32_e32 v3, 31, v2
	v_lshlrev_b64 v[0:1], 10, v[0:1]
	v_lshlrev_b64 v[2:3], 10, v[2:3]
	v_lshl_add_u64 v[0:1], v[76:77], 0, v[0:1]
	v_lshl_add_u64 v[4:5], v[76:77], 0, v[2:3]
	global_load_dwordx4 v[0:3], v[0:1], off
	s_nop 0
	global_load_dwordx4 v[4:7], v[4:5], off
	s_and_b32 s2, s2, 0xffffff00
	v_readlane_b32 s22, v247, 41
	s_add_i32 s87, s22, s2
	s_lshl_b32 s2, s4, 6
	s_add_i32 s87, s87, s2
	s_lshl_b32 s2, s12, 1
	v_readlane_b32 s12, v247, 39
	s_and_b32 s2, s2, 2
	s_add_i32 s88, s12, s5
	s_cmp_le_i32 s2, s3
	s_cselect_b64 s[78:79], -1, 0
	s_cmp_lt_i32 s2, s3
	v_readlane_b32 s38, v247, 9
	s_cselect_b64 s[4:5], -1, 0
	v_readlane_b32 s39, v247, 10
	s_add_u32 s14, s38, s14
	s_addc_u32 s15, s39, 0
	s_lshl_b64 s[10:11], s[10:11], 1
	s_add_u32 s10, s14, s10
	v_lshl_add_u32 v164, v96, 3, s18
	v_lshlrev_b32_e32 v96, 4, v96
	s_addc_u32 s11, s15, s11
	v_lshlrev_b32_e32 v190, 1, v61
	v_lshl_add_u64 v[80:81], v[22:23], 1, s[14:15]
	v_or_b32_e32 v21, s13, v63
	v_or_b32_e32 v36, s0, v61
	v_add_u32_e32 v20, 0x100, v96
	s_movk_i32 s15, 0x110
	v_lshl_add_u64 v[78:79], s[10:11], 0, v[190:191]
	v_lshlrev_b32_e32 v99, 2, v117
	v_mad_u64_u32 v[82:83], s[10:11], v36, s15, v[20:21]
	v_or_b32_e32 v36, s13, v61
	v_add_u32_e32 v67, s16, v99
	v_add_u32_e32 v94, s19, v99
	v_add_u32_e32 v97, s20, v99
	v_add_u32_e32 v99, s12, v99
	v_mul_u32_u24_e32 v37, 0x90, v36
	v_readlane_b32 s12, v247, 40
	s_mulk_i32 s3, 0x880
	s_movk_i32 s14, 0x90
	v_add3_u32 v83, s12, v37, v96
	v_or_b32_e32 v37, s3, v117
	s_mul_i32 s3, s62, 0x88
	v_add_u32_e32 v46, s3, v117
	s_mul_i32 s3, s81, 0x88
	v_add_u32_e32 v47, s3, v117
	s_mul_i32 s3, s63, 0x88
	v_add_u32_e32 v48, s3, v117
	s_mul_i32 s3, s64, 0x88
	v_add_u32_e32 v49, s3, v117
	s_mul_i32 s3, s66, 0x88
	v_add_u32_e32 v50, s3, v117
	s_mul_i32 s3, s65, 0x88
	v_add_u32_e32 v51, s3, v117
	s_mul_i32 s3, s67, 0x88
	v_add_u32_e32 v52, s3, v117
	s_mul_i32 s3, s68, 0x88
	v_add_u32_e32 v53, s3, v117
	s_mul_i32 s3, s70, 0x88
	v_add_u32_e32 v54, s3, v117
	s_mul_i32 s3, s69, 0x88
	v_add_u32_e32 v55, s3, v117
	s_mul_i32 s3, s71, 0x88
	v_add_u32_e32 v56, s3, v117
	s_mul_i32 s3, s72, 0x88
	v_add_u32_e32 v57, s3, v117
	s_mul_i32 s3, s74, 0x88
; __device__ __forceinline__ float fexp(float x) { return __builtin_amdgcn_exp2f(x * 1.44269504f); }
; __device__ __forceinline__ void item_hgrn(const Params& p, int l, int sidx) {
;     ...
;       for (int i = 0; i < 16; ++i) {
;         int tl = qd * 16 + i;
;         float lfv = lf[i], qv = __uint_as_float(qraw[i] << 16);
;         float kin = (t0 + tl < T) ? (1.f - fexp(lfv)) : 0.f;
;         e += lfv;
;         float eq = fexp(fminf(fmaxf(e, -80.f), 80.f));
;         float ek = fexp(fminf(fmaxf(-e, -80.f), 80.f));
;         u16 qb = f2bf(qv * eq), kb = f2bf(kin * ek);
;         Qs[tl * 136 + c] = qb; Ks[tl * 136 + c] = kb;
;         if (i & 1) kpk[i >> 1] |= ((unsigned)kb) << 16; else kpk[i >> 1] = kb;
;       }
;       *reinterpret_cast<uint4*>(KTs + c * 72 + qd * 16) = make_uint4(kpk[0], kpk[1], kpk[2], kpk[3]);
;       *reinterpret_cast<uint4*>(KTs + c * 72 + qd * 16 + 8) = make_uint4(kpk[4], kpk[5], kpk[6], kpk[7]);
;     ...
;         for (int j = 0; j < 4; ++j) {
;           int trow = tt * 16 + fq * 4 + j, scol = st * 16 + fr;
;           float v = (scol <= trow) ? pa[j] : 0.f;
;           Ps[trow * 72 + scol] = f2bf(v);
	v_or_b32_e32 v84, v65, v61
	v_add_u32_e32 v58, s3, v117
	s_mul_i32 s3, s73, 0x88
	v_mad_u64_u32 v[84:85], s[10:11], v84, s14, v[20:21]
	v_add_u32_e32 v59, s3, v117
	v_mul_u32_u24_e32 v85, 0x48, v119
	v_lshl_add_u32 v129, v53, 1, v216
	v_lshl_or_b32 v53, s2, 4, v61
	v_mov_b32_e32 v95, s17
	v_or_b32_e32 v23, s0, v63
	s_mul_i32 s3, s75, 0x88
	v_lshlrev_b32_e32 v119, 1, v85
	v_lshl_add_u32 v136, v59, 1, v216
	v_or_b32_e32 v59, 16, v53
	v_mad_u32_u24 v95, v117, s14, v95
	v_add_u32_e32 v137, s3, v117
	v_lshlrev_b32_e32 v117, 1, v86
	s_movk_i32 s3, 0x100
	v_add_u32_e32 v120, 0x100, v119
	v_lshlrev_b32_e32 v121, 1, v87
	v_lshl_add_u32 v131, v55, 1, v216
	v_mul_lo_u32 v55, v23, s14
	v_lshlrev_b32_e32 v149, 1, v59
	v_readlane_b32 s23, v248, 56
	v_readlane_b32 s24, v248, 57
	v_readlane_b32 s25, v248, 58
	v_readlane_b32 s26, v248, 59
	v_readlane_b32 s27, v248, 60
	v_mad_u32_u24 v101, v36, s15, v20
	v_add_u32_e32 v36, s21, v96
	v_add3_u32 v85, s3, v117, v119
	v_add_u32_e32 v117, v120, v117
	v_add3_u32 v119, s3, v121, v119
	v_add_u32_e32 v120, v120, v121
	v_lshl_add_u32 v121, v37, 1, v216
	v_lshl_add_u32 v122, v46, 1, v216
	v_lshl_add_u32 v123, v47, 1, v216
	v_lshl_add_u32 v124, v48, 1, v216
	v_lshl_add_u32 v125, v49, 1, v216
	v_lshl_add_u32 v126, v50, 1, v216
	v_lshl_add_u32 v127, v51, 1, v216
	v_lshl_add_u32 v128, v52, 1, v216
	v_lshl_add_u32 v130, v54, 1, v216
	v_lshl_add_u32 v132, v56, 1, v216
	v_lshl_add_u32 v134, v57, 1, v216
	v_lshl_add_u32 v135, v58, 1, v216
	v_mul_u32_u24_e32 v37, 0x110, v61
	v_mul_i32_i24_e32 v46, 0x110, v72
	v_mul_i32_i24_e32 v47, 0x110, v70
	v_mul_i32_i24_e32 v48, 0x110, v68
	v_mul_i32_i24_e32 v49, 0x110, v66
	v_mul_i32_i24_e32 v50, 0x110, v64
	v_mul_i32_i24_e32 v51, 0x110, v62
	v_mul_i32_i24_e32 v52, 0x110, v60
	v_mul_u32_u24_e32 v54, 0x110, v53
	v_or_b32_e32 v56, 1, v23
	v_or_b32_e32 v57, 2, v23
	v_or_b32_e32 v58, 3, v23
	v_mul_lo_u32 v166, v22, s14
	v_mul_lo_u32 v22, v22, s15
	v_mul_u32_u24_e32 v168, 0x90, v61
	v_mul_i32_i24_e32 v169, 0x90, v72
	v_mul_i32_i24_e32 v170, 0x90, v70
	v_mul_i32_i24_e32 v171, 0x90, v68
	v_mul_i32_i24_e32 v172, 0x90, v66
	v_mul_i32_i24_e32 v173, 0x90, v64
	v_mul_i32_i24_e32 v174, 0x90, v62
	v_mul_i32_i24_e32 v175, 0x90, v60
	v_lshl_add_u32 v145, v21, 2, s22
	v_lshl_add_u32 v21, v53, 1, s12
	v_add3_u32 v149, s12, v55, v149
	s_add_i32 s2, s91, s13
	s_mov_b32 s83, 0
	v_lshl_add_u32 v137, v137, 1, v216
	v_add_u32_e32 v146, 4, v145
	v_add_u32_e32 v147, 8, v145
	v_add_u32_e32 v148, 12, v145
	v_add_u32_e32 v150, 0x90, v149
	v_add_u32_e32 v151, 0x120, v149
	v_add_u32_e32 v152, 0x1b0, v149
	v_add_u32_e32 v153, 64, v87
	v_add_u32_e32 v154, 64, v86
	s_lshl_b32 s82, s95, 6
	v_add_u32_e32 v155, s13, v63
	v_add_u32_e32 v156, s2, v63
	v_add_u32_e32 v157, v164, v37
	v_add_u32_e32 v158, v164, v46
	v_add_u32_e32 v159, v164, v47
	v_add_u32_e32 v160, v164, v48
	v_add_u32_e32 v161, v164, v49
	v_add_u32_e32 v162, v164, v50
	v_add_u32_e32 v163, v164, v51
	v_add_u32_e32 v164, v164, v52
	v_add_u32_e32 v165, v21, v55
	v_add_u32_e32 v166, v20, v166
	v_add_u32_e32 v167, v36, v22
	v_add_u32_e32 v168, v20, v168
	v_add_u32_e32 v169, v20, v169
	v_add_u32_e32 v170, v20, v170
	v_add_u32_e32 v171, v20, v171
	v_add_u32_e32 v172, v20, v172
	v_add_u32_e32 v173, v20, v173
	v_add_u32_e32 v174, v20, v174
	v_add_u32_e32 v175, v20, v175
	v_add_u32_e32 v176, v20, v54
	s_mov_b32 s94, s86
	v_cmp_eq_u32_e64 s[10:11], 0, v61
	v_cmp_gt_i32_e64 s[12:13], v53, v23
	v_cmp_gt_i32_e64 s[14:15], v53, v56
	v_cmp_gt_i32_e64 s[16:17], v53, v57
	v_cmp_gt_i32_e64 s[18:19], v53, v58
	v_cmp_gt_i32_e64 s[20:21], v59, v23
	v_cmp_gt_i32_e64 s[22:23], v59, v56
	v_cmp_gt_i32_e64 s[24:25], v59, v57
	v_cmp_gt_i32_e64 s[26:27], v59, v58
	v_readlane_b32 s30, v248, 63
	v_readlane_b32 s31, v247, 0
	v_readlane_b32 s40, v247, 11
	v_readlane_b32 s41, v247, 12
	v_readlane_b32 s42, v247, 13
	v_readlane_b32 s43, v247, 14
	v_readlane_b32 s46, v247, 17
	v_readlane_b32 s47, v247, 18
	v_readlane_b32 s48, v247, 19
	v_readlane_b32 s49, v247, 20
	v_readlane_b32 s50, v247, 21
	v_readlane_b32 s51, v247, 22
	s_waitcnt vmcnt(0)
	s_branch .LBB0_802

; __device__ __forceinline__ float fexp(float x) { return __builtin_amdgcn_exp2f(x * 1.44269504f); }
; __device__ __forceinline__ void item_hgrn(const Params& p, int l, int sidx) {
;     ...
;     {
;       float run = 0.f;
; #pragma unroll
;       for (int i = 0; i < 16; ++i) { if (t0 + qd * 16 + i >= T) { lf[i] = 0.f; qraw[i] = 0u; } run += lf[i]; }
;       tot[qd * 128 + c] = run;
;     }
; #pragma unroll
;     for (int i = 0; i < 2; ++i) {
;       int e = tid + i * NTHR, s = e >> 4, dv0 = (e & 15) * 8;
;       unsigned w[4] = {vraw[i].x, vraw[i].y, vraw[i].z, vraw[i].w};
;       if (t0 + s >= T) { w[0] = 0u; w[1] = 0u; w[2] = 0u; w[3] = 0u; }
; #pragma unroll
;       for (int k = 0; k < 4; ++k) {
;         VTs[(dv0 + 2 * k) * 72 + s] = (u16)(w[k] & 0xffffu);
;         VTs[(dv0 + 2 * k + 1) * 72 + s] = (u16)(w[k] >> 16);
;       }
;     }
;     __syncthreads();
;     {
;       float t0v = tot[c], t1v = tot[128 + c], t2v = tot[256 + c], t3v = tot[384 + c];
;       float r = t0v + t1v;
;       float e = (qd == 0 ? 0.f : qd == 1 ? t0v : qd == 2 ? r : r + t2v) - r;
;       if (qd == 0) er[c] = fexp(fmaxf(r, -80.f));
;       if (qd == 1) el[c] = fexp(fmaxf(t2v + t3v, -80.f));
.LBB0_802:
	s_add_i32 s92, s0, s83
	s_cmp_lt_i32 s92, s86
	s_cselect_b64 s[28:29], -1, 0
	s_add_i32 s2, s92, 1
	s_cmp_lt_i32 s2, s86
	s_cselect_b64 s[30:31], -1, 0
	s_add_i32 s2, s92, 2
	s_cmp_lt_i32 s2, s86
	s_cselect_b64 s[34:35], -1, 0
	s_add_i32 s2, s92, 3
	s_cmp_lt_i32 s2, s86
	s_cselect_b64 s[36:37], -1, 0
	s_add_i32 s2, s92, 4
	s_cmp_lt_i32 s2, s86
	s_cselect_b64 s[38:39], -1, 0
	s_add_i32 s2, s92, 5
	s_cmp_lt_i32 s2, s86
	s_cselect_b64 s[40:41], -1, 0
	s_add_i32 s2, s92, 6
	s_cmp_lt_i32 s2, s86
	s_cselect_b64 s[44:45], -1, 0
	s_add_i32 s2, s92, 7
	s_cmp_lt_i32 s2, s86
	s_cselect_b64 s[46:47], -1, 0
	s_add_i32 s2, s92, 8
	s_cmp_lt_i32 s2, s86
	v_cndmask_b32_e64 v88, 0, v88, s[28:29]
	s_cselect_b64 s[48:49], -1, 0
	s_add_i32 s2, s92, 9
	v_add_f32_e32 v20, 0, v88
	v_cndmask_b32_e64 v90, 0, v90, s[30:31]
	s_cmp_lt_i32 s2, s86
	v_add_f32_e32 v20, v20, v90
	v_cndmask_b32_e64 v92, 0, v92, s[34:35]
	s_cselect_b64 s[50:51], -1, 0
	s_add_i32 s2, s92, 10
	v_add_f32_e32 v20, v92, v20
	v_cndmask_b32_e64 v98, 0, v98, s[36:37]
	s_cmp_lt_i32 s2, s86
	v_add_f32_e32 v20, v98, v20
	v_cndmask_b32_e64 v102, 0, v102, s[38:39]
	s_cselect_b64 s[52:53], -1, 0
	s_add_i32 s2, s92, 11
	v_add_f32_e32 v20, v102, v20
	v_cndmask_b32_e64 v104, 0, v104, s[40:41]
	s_cmp_lt_i32 s2, s86
	s_mov_b64 s[8:9], s[54:55]
	v_add_f32_e32 v20, v104, v20
	v_cndmask_b32_e64 v106, 0, v106, s[44:45]
	s_cselect_b64 s[54:55], -1, 0
	s_add_i32 s2, s92, 12
	v_add_f32_e32 v20, v106, v20
	v_cndmask_b32_e64 v108, 0, v108, s[46:47]
	s_cmp_lt_i32 s2, s86
	v_add_f32_e32 v20, v108, v20
	v_cndmask_b32_e64 v110, 0, v110, s[48:49]
	s_cselect_b64 s[56:57], -1, 0
	s_add_i32 s2, s92, 13
	v_add_f32_e32 v20, v110, v20
	v_cndmask_b32_e64 v112, 0, v112, s[50:51]
	s_cmp_lt_i32 s2, s86
	v_add_f32_e32 v20, v112, v20
	v_cndmask_b32_e64 v114, 0, v114, s[52:53]
	s_cselect_b64 s[58:59], -1, 0
	s_add_i32 s2, s92, 14
	v_add_f32_e32 v20, v114, v20
	v_cndmask_b32_e64 v116, 0, v116, s[54:55]
	s_cmp_lt_i32 s2, s86
	v_add_f32_e32 v20, v116, v20
	v_cndmask_b32_e64 v133, 0, v133, s[56:57]
	s_cselect_b64 s[60:61], -1, 0
	s_add_i32 s2, s92, 15
	v_add_f32_e32 v20, v133, v20
	v_cndmask_b32_e64 v139, 0, v139, s[58:59]
	s_cmp_lt_i32 s2, s86
	v_add_f32_e32 v20, v139, v20
	v_cndmask_b32_e64 v141, 0, v141, s[60:61]
	s_cselect_b64 s[42:43], -1, 0
	v_add_f32_e32 v20, v141, v20
	v_cndmask_b32_e64 v143, 0, v143, s[42:43]
	v_add_f32_e32 v20, v143, v20
	ds_write_b32 v67, v20
	v_cmp_le_i32_e32 vcc, s94, v86
	v_mov_b32_e32 v20, v3
	v_mov_b32_e32 v21, v2
	v_mov_b32_e32 v22, v1
	v_mov_b32_e32 v23, v0
	s_and_saveexec_b64 s[2:3], vcc
	v_mov_b32_e32 v20, 0
	v_mov_b32_e32 v21, 0
	v_mov_b32_e32 v22, 0
	v_mov_b32_e32 v23, 0
	s_or_b64 exec, exec, s[2:3]
	ds_write_b16 v85, v23 offset:53248
	ds_write_b16_d16_hi v117, v23 offset:53392
	ds_write_b16 v85, v22 offset:53536
	ds_write_b16_d16_hi v117, v22 offset:53680
	ds_write_b16 v85, v21 offset:53824
	ds_write_b16_d16_hi v117, v21 offset:53968
	ds_write_b16 v85, v20 offset:54112
	ds_write_b16_d16_hi v117, v20 offset:54256
	v_cmp_le_i32_e32 vcc, s94, v87
	v_mov_b32_e32 v20, v7
	v_mov_b32_e32 v21, v6
	v_mov_b32_e32 v22, v5
	v_mov_b32_e32 v23, v4
	s_and_saveexec_b64 s[2:3], vcc
	v_mov_b32_e32 v20, 0
	v_mov_b32_e32 v21, 0
	v_mov_b32_e32 v22, 0
	v_mov_b32_e32 v23, 0
	s_or_b64 exec, exec, s[2:3]
	ds_write_b16 v119, v23 offset:53248
	ds_write_b16_d16_hi v120, v23 offset:53392
	ds_write_b16 v119, v22 offset:53536
	ds_write_b16_d16_hi v120, v22 offset:53680
	ds_write_b16 v119, v21 offset:53824
	ds_write_b16_d16_hi v120, v21 offset:53968
	ds_write_b16 v119, v20 offset:54112
	ds_write_b16_d16_hi v120, v20 offset:54256
	s_waitcnt lgkmcnt(0)
	s_barrier
	ds_read2st64_b32 v[20:21], v94 offset1:2
	ds_read2st64_b32 v[22:23], v94 offset0:4 offset1:6
	s_andn2_b64 vcc, exec, s[76:77]
	s_waitcnt lgkmcnt(1)
	v_add_f32_e32 v21, v20, v21
	s_cbranch_vccnz .LBB0_808
	v_max_f32_e32 v36, v21, v21
	v_max_f32_e32 v36, 0xc2a00000, v36
	v_mul_f32_e32 v36, 0x3fb8aa3b, v36
	v_exp_f32_e32 v36, v36
	ds_write_b32 v97, v36

; __device__ __forceinline__ void gemm_run(const Params& p, int l, int kind, int single) {
;     ...
; #pragma unroll
;   for (int a = 0; a < 2; ++a)
; #pragma unroll
;     for (int b = 0; b < 2; ++b)
; #pragma unroll
;       for (int m = 0; m < 4; ++m)
; #pragma unroll
;         for (int n = 0; n < 2; ++n) acc[a][b][m][n] = f32x4{0.f, 0.f, 0.f, 0.f};
;   bf16x8 At[4][2], B0[2][2], B1[2][2];
;   const char* cA = cur.A; const char* cB = cur.B;
;   unsigned vc0 = (unsigned)(sR[0] * cur.ld + sC[0]) * 2u, vc1 = (unsigned)(sR[1] * cur.ld + sC[1]) * 2u;
;   size_t hc = (size_t)128 * cur.ld * 2;
.LBB0_906:
	s_ashr_i32 s15, s14, 31
	s_lshl_b64 s[20:21], s[14:15], 8
	s_add_i32 s3, s2, -2
	v_mul_lo_u32 v0, s14, v199
	s_add_u32 s12, s12, 0x80
	v_add_lshl_u32 v200, v0, v218, 1
	v_mul_lo_u32 v0, s14, v219
	s_addc_u32 s13, s13, 0
	v_add_lshl_u32 v202, v0, v220, 1
	v_mov_b32_e32 v129, v191
	s_add_u32 s22, s22, 0x100
	v_mov_b32_e32 v0, 0
	v_mov_b32_e32 v201, v191
	v_mov_b32_e32 v203, v191
	s_addc_u32 s23, s23, 0
	v_lshl_add_u64 v[130:131], s[10:11], 0, v[190:191]
	v_lshl_add_u64 v[132:133], s[10:11], 0, v[128:129]
	s_mov_b32 s15, 0
	v_mov_b32_e32 v1, 0
	v_mov_b64_e32 v[2:3], 0
	v_mov_b64_e32 v[4:5], 0
	v_mov_b64_e32 v[6:7], 0
	v_mov_b64_e32 v[8:9], 0
	v_mov_b64_e32 v[10:11], 0
	v_mov_b64_e32 v[12:13], 0
	v_mov_b64_e32 v[14:15], 0
	v_mov_b64_e32 v[16:17], 0
	v_mov_b64_e32 v[18:19], 0
	v_mov_b64_e32 v[20:21], 0
	v_mov_b64_e32 v[22:23], 0
	v_mov_b64_e32 v[24:25], 0
	v_mov_b64_e32 v[26:27], 0
	v_mov_b64_e32 v[28:29], 0
	v_mov_b64_e32 v[30:31], 0
	v_mov_b64_e32 v[32:33], 0
	v_mov_b64_e32 v[34:35], 0
	v_mov_b64_e32 v[36:37], 0
	v_mov_b64_e32 v[38:39], 0
	v_mov_b64_e32 v[40:41], 0
	v_mov_b64_e32 v[42:43], 0
	v_mov_b64_e32 v[44:45], 0
	v_mov_b64_e32 v[46:47], 0
	v_mov_b64_e32 v[48:49], 0
	v_mov_b64_e32 v[50:51], 0
	v_mov_b64_e32 v[52:53], 0
	v_mov_b64_e32 v[54:55], 0
	v_mov_b64_e32 v[56:57], 0
	v_mov_b64_e32 v[58:59], 0
	v_mov_b64_e32 v[60:61], 0
	v_mov_b64_e32 v[62:63], 0
	v_mov_b64_e32 v[64:65], 0
	v_mov_b64_e32 v[66:67], 0
	v_mov_b64_e32 v[68:69], 0
	v_mov_b64_e32 v[70:71], 0
	v_mov_b64_e32 v[72:73], 0
	v_mov_b64_e32 v[74:75], 0
	v_mov_b64_e32 v[76:77], 0
	v_mov_b64_e32 v[78:79], 0
	v_mov_b64_e32 v[80:81], 0
	v_mov_b64_e32 v[82:83], 0
	v_mov_b64_e32 v[84:85], 0
	v_mov_b64_e32 v[86:87], 0
	v_mov_b64_e32 v[88:89], 0
	v_mov_b64_e32 v[90:91], 0
	v_mov_b64_e32 v[92:93], 0
	v_mov_b64_e32 v[94:95], 0
	v_mov_b64_e32 v[96:97], 0
	v_mov_b64_e32 v[98:99], 0
	v_mov_b64_e32 v[100:101], 0
	v_mov_b64_e32 v[102:103], 0
	v_mov_b64_e32 v[104:105], 0
	v_mov_b64_e32 v[106:107], 0
	v_mov_b64_e32 v[108:109], 0
	v_mov_b64_e32 v[110:111], 0
	v_mov_b64_e32 v[112:113], 0
	v_mov_b64_e32 v[114:115], 0
	v_mov_b64_e32 v[116:117], 0
	v_mov_b64_e32 v[118:119], 0
	v_mov_b64_e32 v[120:121], 0
	v_mov_b64_e32 v[122:123], 0
	v_mov_b64_e32 v[124:125], 0
	v_mov_b64_e32 v[126:127], 0
	s_branch .LBB0_908

; #define G_STAGE(bufoff, gbase, v0, v1) do { \
;     __builtin_amdgcn_global_load_lds((const unsigned*)((const char*)(gbase) + (v0)), (LAS unsigned*)(lds + (bufoff) + ldsw), 16, 0, 0); \
;     __builtin_amdgcn_global_load_lds((const unsigned*)((const char*)(gbase) + (v1)), (LAS unsigned*)(lds + (bufoff) + ldsw + 8192), 16, 0, 0); } while (0)
; #define G_LDA(dst, b, h) do { _Pragma("unroll") for (int m = 0; m < 4; ++m) _Pragma("unroll") for (int k = 0; k < 2; ++k) dst[m][k] = *(const LAS bf16x8*)(lds + G_SA(b, h) + aoff + m * 2048 + k * 1024); } while (0)
; #define G_LDB(dst, b, h) do { _Pragma("unroll") for (int n = 0; n < 2; ++n) _Pragma("unroll") for (int k = 0; k < 2; ++k) dst[n][k] = *(const LAS bf16x8*)(lds + G_SB(b, h) + boff + n * 2048 + k * 1024); } while (0)
; #define G_MMA(ai, bj, At, Bt) do { __builtin_amdgcn_s_setprio(1); _Pragma("unroll") for (int m = 0; m < 4; ++m) _Pragma("unroll") for (int n = 0; n < 2; ++n) _Pragma("unroll") for (int k = 0; k < 2; ++k) \
;     acc[ai][bj][m][n] = __builtin_amdgcn_mfma_f32_16x16x32_bf16(Bt[n][k], At[m][k], acc[ai][bj][m][n], 0, 0, 0); __builtin_amdgcn_s_setprio(0); } while (0)
; __device__ __forceinline__ void gemm_run(const Params& p, int l, int kind, int single) {
;     ...
;     for (int t = 0; t < nt; t += 2) {
;       const bool last = (t == nt - 2);
;       const char* a1 = cA + (size_t)(t + 1) * kstep;
;       const char* a2 = last ? nA : cA + (size_t)(t + 2) * kstep; const char* b2 = last ? nB : cB + (size_t)(t + 2) * kstep;
;       const char* a3 = a2 + kstep; const char* b3 = b2 + kstep;
;       const unsigned w0 = last ? vn0 : vc0, w1 = last ? vn1 : vc1; const size_t h2 = last ? hn : hc;
;       G_LDB(B0, 0, 0); G_SCHED; G_LDA(At, 0, 0); G_STAGE(G_SA(1, 1), a1 + hc, vc0, vc1);
;       G_WAIT_L(8); G_BAR; G_WAIT_L(0); G_MMA(0, 0, At, B0); G_BAR; G_SCHED;
;       G_LDB(B1, 0, 1); G_STAGE(G_SB(0, 0), b2, w0, w1);
;       G_BAR; G_WAIT_L(0); G_MMA(0, 1, At, B1); G_BAR;
;       G_LDA(At, 0, 1); G_STAGE(G_SA(0, 0), a2, w0, w1);
;       G_BAR; G_WAIT_L(0); G_MMA(1, 0, At, B0); G_BAR; G_SCHED;
;     ...
;     for (int a = 0; a < 2; ++a)
; #pragma unroll
;       for (int b = 0; b < 2; ++b)
; #pragma unroll
;         for (int m = 0; m < 4; ++m)
; #pragma unroll
;           for (int n = 0; n < 2; ++n) acc[a][b][m][n] = f32x4{0.f, 0.f, 0.f, 0.f};
;     cur = nxt; cA = nA; cB = nB; vc0 = vn0; vc1 = vn1; hc = hn; ++ui;
.LBB0_1011:
	s_add_u32 s12, s12, 0x40080
	s_addc_u32 s13, s13, 0
	s_add_u32 s1, s14, 0x100
	v_mov_b32_e32 v0, 0
	s_addc_u32 s5, s15, 0
	s_mov_b32 s27, -2
	v_mov_b32_e32 v1, 0
	v_mov_b64_e32 v[2:3], 0
	v_mov_b64_e32 v[4:5], 0
	v_mov_b64_e32 v[6:7], 0
	v_mov_b64_e32 v[8:9], 0
	v_mov_b64_e32 v[10:11], 0
	v_mov_b64_e32 v[12:13], 0
	v_mov_b64_e32 v[14:15], 0
	v_mov_b64_e32 v[16:17], 0
	v_mov_b64_e32 v[18:19], 0
	v_mov_b64_e32 v[20:21], 0
	v_mov_b64_e32 v[22:23], 0
	v_mov_b64_e32 v[24:25], 0
	v_mov_b64_e32 v[26:27], 0
	v_mov_b64_e32 v[28:29], 0
	v_mov_b64_e32 v[30:31], 0
	v_mov_b64_e32 v[32:33], 0
	v_mov_b64_e32 v[34:35], 0
	v_mov_b64_e32 v[36:37], 0
	v_mov_b64_e32 v[38:39], 0
	v_mov_b64_e32 v[40:41], 0
	v_mov_b64_e32 v[42:43], 0
	v_mov_b64_e32 v[44:45], 0
	v_mov_b64_e32 v[46:47], 0
	v_mov_b64_e32 v[48:49], 0
	v_mov_b64_e32 v[50:51], 0
	v_mov_b64_e32 v[52:53], 0
	v_mov_b64_e32 v[54:55], 0
	v_mov_b64_e32 v[56:57], 0
	v_mov_b64_e32 v[58:59], 0
	v_mov_b64_e32 v[60:61], 0
	v_mov_b64_e32 v[62:63], 0
	v_mov_b64_e32 v[64:65], 0
	v_mov_b64_e32 v[66:67], 0
	v_mov_b64_e32 v[68:69], 0
	v_mov_b64_e32 v[70:71], 0
	v_mov_b64_e32 v[72:73], 0
	v_mov_b64_e32 v[74:75], 0
	v_mov_b64_e32 v[76:77], 0
	v_mov_b64_e32 v[78:79], 0
	v_mov_b64_e32 v[80:81], 0
	v_mov_b64_e32 v[82:83], 0
	v_mov_b64_e32 v[84:85], 0
	v_mov_b64_e32 v[86:87], 0
	v_mov_b64_e32 v[88:89], 0
	v_mov_b64_e32 v[90:91], 0
	v_mov_b64_e32 v[92:93], 0
	v_mov_b64_e32 v[94:95], 0
	v_mov_b64_e32 v[96:97], 0
	v_mov_b64_e32 v[98:99], 0
	v_mov_b64_e32 v[100:101], 0
	v_mov_b64_e32 v[102:103], 0
	v_mov_b64_e32 v[104:105], 0
	v_mov_b64_e32 v[106:107], 0
	v_mov_b64_e32 v[108:109], 0
	v_mov_b64_e32 v[110:111], 0
	v_mov_b64_e32 v[112:113], 0
	v_mov_b64_e32 v[114:115], 0
	v_mov_b64_e32 v[116:117], 0
	v_mov_b64_e32 v[118:119], 0
	v_mov_b64_e32 v[120:121], 0
	v_mov_b64_e32 v[122:123], 0
	v_mov_b64_e32 v[124:125], 0
	v_mov_b64_e32 v[126:127], 0
.LBB0_1012:
	s_add_u32 s14, s12, 0xfffc0080
	s_addc_u32 s15, s13, -1
	s_cmp_eq_u32 s27, 12
	s_cselect_b32 s17, s9, s15
	s_cselect_b32 s16, s8, s14
	s_cselect_b32 s15, s11, s5
	s_cselect_b32 s14, s10, s1
	s_add_i32 s28, s89, 0x100
	v_add_u32_e32 v138, s28, v140
	ds_read_b128 v[134:137], v138
	ds_read_b128 v[142:145], v138 offset:1024
	ds_read_b128 v[146:149], v138 offset:2048
	ds_read_b128 v[150:153], v138 offset:3072
	v_lshl_add_u64 v[138:139], s[12:13], 0, v[130:131]
	s_add_i32 m0, s18, 0xc000
	ds_read_b128 v[154:157], v141
	ds_read_b128 v[158:161], v141 offset:1024
	ds_read_b128 v[162:165], v141 offset:2048
	ds_read_b128 v[166:169], v141 offset:3072
	ds_read_b128 v[170:173], v141 offset:4096
	ds_read_b128 v[174:177], v141 offset:5120
	ds_read_b128 v[178:181], v141 offset:6144
	ds_read_b128 v[182:185], v141 offset:7168
	global_load_lds_dwordx4 v[138:139], off
	v_lshl_add_u64 v[138:139], s[12:13], 0, v[132:133]
	s_add_i32 m0, s18, 0xe000
	s_nop 0
	global_load_lds_dwordx4 v[138:139], off
	s_waitcnt lgkmcnt(8)
	s_barrier
	s_waitcnt lgkmcnt(0)
	s_setprio 1
	s_waitcnt lgkmcnt(0)
	v_mfma_f32_16x16x32_bf16 v[124:127], v[134:137], v[154:157], v[124:127]
	v_mfma_f32_16x16x32_bf16 v[120:123], v[146:149], v[154:157], v[120:123]
	v_mfma_f32_16x16x32_bf16 v[116:119], v[134:137], v[162:165], v[116:119]
	v_mfma_f32_16x16x32_bf16 v[112:115], v[146:149], v[162:165], v[112:115]
	v_mfma_f32_16x16x32_bf16 v[108:111], v[134:137], v[170:173], v[108:111]
	v_mfma_f32_16x16x32_bf16 v[100:103], v[146:149], v[170:173], v[100:103]
	v_mfma_f32_16x16x32_bf16 v[84:87], v[134:137], v[178:181], v[84:87]
	v_mfma_f32_16x16x32_bf16 v[72:75], v[146:149], v[178:181], v[72:75]
	v_mfma_f32_16x16x32_bf16 v[124:127], v[142:145], v[158:161], v[124:127]
	v_mfma_f32_16x16x32_bf16 v[120:123], v[150:153], v[158:161], v[120:123]
	v_mfma_f32_16x16x32_bf16 v[116:119], v[142:145], v[166:169], v[116:119]
	v_mfma_f32_16x16x32_bf16 v[112:115], v[150:153], v[166:169], v[112:115]
	v_mfma_f32_16x16x32_bf16 v[108:111], v[142:145], v[174:177], v[108:111]
	v_mfma_f32_16x16x32_bf16 v[100:103], v[150:153], v[174:177], v[100:103]
	v_mfma_f32_16x16x32_bf16 v[84:87], v[142:145], v[182:185], v[84:87]
	v_mfma_f32_16x16x32_bf16 v[72:75], v[150:153], v[182:185], v[72:75]
	s_setprio 0
	s_barrier
	s_add_i32 s30, s90, 0x100
	v_add_u32_e32 v138, s30, v140
	s_add_i32 s28, s28, s3
	ds_read_b128 v[200:203], v138
	ds_read_b128 v[204:207], v138 offset:1024
	ds_read_b128 v[218:221], v138 offset:2048
	ds_read_b128 v[222:225], v138 offset:3072
	v_lshl_add_u64 v[138:139], s[14:15], 0, v[190:191]
	s_mov_b32 m0, s28
	v_lshl_add_u64 v[186:187], s[14:15], 0, v[128:129]
	global_load_lds_dwordx4 v[138:139], off
	s_add_i32 m0, s28, 0x2000
	s_nop 0
	global_load_lds_dwordx4 v[186:187], off
	s_barrier
	s_waitcnt lgkmcnt(0)
	s_setprio 1
	s_waitcnt lgkmcnt(0)
	v_mfma_f32_16x16x32_bf16 v[104:107], v[200:203], v[154:157], v[104:107]
	v_mfma_f32_16x16x32_bf16 v[96:99], v[218:221], v[154:157], v[96:99]
	v_mfma_f32_16x16x32_bf16 v[92:95], v[200:203], v[162:165], v[92:95]
	v_mfma_f32_16x16x32_bf16 v[88:91], v[218:221], v[162:165], v[88:91]
	v_mfma_f32_16x16x32_bf16 v[80:83], v[200:203], v[170:173], v[80:83]
	v_mfma_f32_16x16x32_bf16 v[76:79], v[218:221], v[170:173], v[76:79]
	v_mfma_f32_16x16x32_bf16 v[68:71], v[200:203], v[178:181], v[68:71]
	v_mfma_f32_16x16x32_bf16 v[64:67], v[218:221], v[178:181], v[64:67]
	v_mfma_f32_16x16x32_bf16 v[104:107], v[204:207], v[158:161], v[104:107]
	v_mfma_f32_16x16x32_bf16 v[96:99], v[222:225], v[158:161], v[96:99]
	v_mfma_f32_16x16x32_bf16 v[92:95], v[204:207], v[166:169], v[92:95]
	v_mfma_f32_16x16x32_bf16 v[88:91], v[222:225], v[166:169], v[88:91]
	v_mfma_f32_16x16x32_bf16 v[80:83], v[204:207], v[174:177], v[80:83]
	v_mfma_f32_16x16x32_bf16 v[76:79], v[222:225], v[174:177], v[76:79]
	v_mfma_f32_16x16x32_bf16 v[68:71], v[204:207], v[182:185], v[68:71]
	v_mfma_f32_16x16x32_bf16 v[64:67], v[222:225], v[182:185], v[64:67]
	s_setprio 0
	s_mov_b32 m0, s18
	v_lshl_add_u64 v[226:227], s[16:17], 0, v[190:191]
	s_barrier
; #define G_STAGE(bufoff, gbase, v0, v1) do { \
;     __builtin_amdgcn_global_load_lds((const unsigned*)((const char*)(gbase) + (v0)), (LAS unsigned*)(lds + (bufoff) + ldsw), 16, 0, 0); \
;     __builtin_amdgcn_global_load_lds((const unsigned*)((const char*)(gbase) + (v1)), (LAS unsigned*)(lds + (bufoff) + ldsw + 8192), 16, 0, 0); } while (0)
; #define G_LDA(dst, b, h) do { _Pragma("unroll") for (int m = 0; m < 4; ++m) _Pragma("unroll") for (int k = 0; k < 2; ++k) dst[m][k] = *(const LAS bf16x8*)(lds + G_SA(b, h) + aoff + m * 2048 + k * 1024); } while (0)
; #define G_LDB(dst, b, h) do { _Pragma("unroll") for (int n = 0; n < 2; ++n) _Pragma("unroll") for (int k = 0; k < 2; ++k) dst[n][k] = *(const LAS bf16x8*)(lds + G_SB(b, h) + boff + n * 2048 + k * 1024); } while (0)
; #define G_MMA(ai, bj, At, Bt) do { __builtin_amdgcn_s_setprio(1); _Pragma("unroll") for (int m = 0; m < 4; ++m) _Pragma("unroll") for (int n = 0; n < 2; ++n) _Pragma("unroll") for (int k = 0; k < 2; ++k) \
;     acc[ai][bj][m][n] = __builtin_amdgcn_mfma_f32_16x16x32_bf16(Bt[n][k], At[m][k], acc[ai][bj][m][n], 0, 0, 0); __builtin_amdgcn_s_setprio(0); } while (0)
; #define G_WAIT_V(n) asm volatile("s_waitcnt vmcnt(" #n ")" ::: "memory")
; #define G_WAIT_L(n) asm volatile("s_waitcnt lgkmcnt(" #n ")" ::: "memory")
; #define G_BAR __builtin_amdgcn_s_barrier()
; #define G_SCHED __builtin_amdgcn_sched_barrier(0)
; __device__ __forceinline__ void gemm_run(const Params& p, int l, int kind, int single) {
;     ...
;       G_LDB(B1, 0, 1); G_STAGE(G_SB(0, 0), b2, w0, w1);
;       G_BAR; G_WAIT_L(0); G_MMA(0, 1, At, B1); G_BAR;
;       G_LDA(At, 0, 1); G_STAGE(G_SA(0, 0), a2, w0, w1);
;       G_BAR; G_WAIT_L(0); G_MMA(1, 0, At, B0); G_BAR; G_SCHED;
;       G_STAGE(G_SB(0, 1), b2 + h2, w0, w1);
;       G_WAIT_V(6); G_BAR; G_MMA(1, 1, At, B1); G_BAR;
;       G_LDB(B0, 1, 0); G_SCHED; G_LDA(At, 1, 0); G_STAGE(G_SA(0, 1), a2 + h2, w0, w1);
;       G_WAIT_L(8); G_BAR; G_WAIT_L(0); G_MMA(0, 0, At, B0); G_BAR; G_SCHED;
;       G_LDB(B1, 1, 1); G_STAGE(G_SB(1, 0), b3, w0, w1);
;       G_BAR; G_WAIT_L(0); G_MMA(0, 1, At, B1); G_BAR;
;       G_LDA(At, 1, 1); G_STAGE(G_SA(1, 0), a3, w0, w1);
	ds_read_b128 v[154:157], v141 offset:16384
	ds_read_b128 v[158:161], v141 offset:17408
	ds_read_b128 v[162:165], v141 offset:18432
	ds_read_b128 v[166:169], v141 offset:19456
	ds_read_b128 v[170:173], v141 offset:20480
	ds_read_b128 v[174:177], v141 offset:21504
	ds_read_b128 v[178:181], v141 offset:22528
	ds_read_b128 v[182:185], v141 offset:23552
	global_load_lds_dwordx4 v[226:227], off
	v_lshl_add_u64 v[228:229], s[16:17], 0, v[128:129]
	s_mov_b32 m0, s19
	s_nop 0
	global_load_lds_dwordx4 v[228:229], off
	s_barrier
	s_waitcnt lgkmcnt(0)
	s_setprio 1
	s_waitcnt lgkmcnt(0)
	v_mfma_f32_16x16x32_bf16 v[60:63], v[134:137], v[154:157], v[60:63]
	v_mfma_f32_16x16x32_bf16 v[56:59], v[146:149], v[154:157], v[56:59]
	v_mfma_f32_16x16x32_bf16 v[52:55], v[134:137], v[162:165], v[52:55]
	v_mfma_f32_16x16x32_bf16 v[48:51], v[146:149], v[162:165], v[48:51]
	v_mfma_f32_16x16x32_bf16 v[44:47], v[134:137], v[170:173], v[44:47]
	v_mfma_f32_16x16x32_bf16 v[36:39], v[146:149], v[170:173], v[36:39]
	v_mfma_f32_16x16x32_bf16 v[28:31], v[134:137], v[178:181], v[28:31]
	v_mfma_f32_16x16x32_bf16 v[16:19], v[146:149], v[178:181], v[16:19]
	v_mfma_f32_16x16x32_bf16 v[60:63], v[142:145], v[158:161], v[60:63]
	v_mfma_f32_16x16x32_bf16 v[56:59], v[150:153], v[158:161], v[56:59]
	v_mfma_f32_16x16x32_bf16 v[52:55], v[142:145], v[166:169], v[52:55]
	v_mfma_f32_16x16x32_bf16 v[48:51], v[150:153], v[166:169], v[48:51]
	v_mfma_f32_16x16x32_bf16 v[44:47], v[142:145], v[174:177], v[44:47]
	v_mfma_f32_16x16x32_bf16 v[36:39], v[150:153], v[174:177], v[36:39]
	v_mfma_f32_16x16x32_bf16 v[28:31], v[142:145], v[182:185], v[28:31]
	v_mfma_f32_16x16x32_bf16 v[16:19], v[150:153], v[182:185], v[16:19]
	s_setprio 0
	s_barrier
	s_add_u32 s28, s14, 0x40000
	s_addc_u32 s29, s15, 0
	s_add_i32 s30, s30, s3
	v_lshl_add_u64 v[134:135], s[28:29], 0, v[190:191]
	s_mov_b32 m0, s30
	s_nop 0
	global_load_lds_dwordx4 v[134:135], off
	v_lshl_add_u64 v[134:135], s[28:29], 0, v[128:129]
	s_add_i32 m0, s30, 0x2000
	s_nop 0
	global_load_lds_dwordx4 v[134:135], off
	s_waitcnt vmcnt(6)
	s_barrier
	s_setprio 1
	v_mfma_f32_16x16x32_bf16 v[40:43], v[200:203], v[154:157], v[40:43]
	v_mfma_f32_16x16x32_bf16 v[32:35], v[218:221], v[154:157], v[32:35]
	v_mfma_f32_16x16x32_bf16 v[24:27], v[200:203], v[162:165], v[24:27]
	v_mfma_f32_16x16x32_bf16 v[20:23], v[218:221], v[162:165], v[20:23]
	v_mfma_f32_16x16x32_bf16 v[12:15], v[200:203], v[170:173], v[12:15]
	v_mfma_f32_16x16x32_bf16 v[8:11], v[218:221], v[170:173], v[8:11]
	v_mfma_f32_16x16x32_bf16 v[4:7], v[200:203], v[178:181], v[4:7]
	v_mfma_f32_16x16x32_bf16 v[0:3], v[218:221], v[178:181], v[0:3]
	v_mfma_f32_16x16x32_bf16 v[40:43], v[204:207], v[158:161], v[40:43]
	v_mfma_f32_16x16x32_bf16 v[32:35], v[222:225], v[158:161], v[32:35]
	v_mfma_f32_16x16x32_bf16 v[24:27], v[204:207], v[166:169], v[24:27]
	v_mfma_f32_16x16x32_bf16 v[20:23], v[222:225], v[166:169], v[20:23]
	v_mfma_f32_16x16x32_bf16 v[12:15], v[204:207], v[174:177], v[12:15]
	v_mfma_f32_16x16x32_bf16 v[8:11], v[222:225], v[174:177], v[8:11]
	v_mfma_f32_16x16x32_bf16 v[4:7], v[204:207], v[182:185], v[4:7]
	v_mfma_f32_16x16x32_bf16 v[0:3], v[222:225], v[182:185], v[0:3]
	s_setprio 0
	s_add_i32 s28, s91, 0x100
	v_add_u32_e32 v150, s28, v140
	s_barrier
	ds_read_b128 v[134:137], v150
	ds_read_b128 v[142:145], v150 offset:1024
	ds_read_b128 v[146:149], v150 offset:2048
	ds_read_b128 v[150:153], v150 offset:3072
	s_add_u32 s16, s16, 0x40000
	s_addc_u32 s17, s17, 0
	s_mov_b32 m0, s20
	v_lshl_add_u64 v[200:201], s[16:17], 0, v[190:191]
	ds_read_b128 v[154:157], v141 offset:32768
	ds_read_b128 v[158:161], v141 offset:33792
	ds_read_b128 v[162:165], v141 offset:34816
	ds_read_b128 v[166:169], v141 offset:35840
	ds_read_b128 v[170:173], v141 offset:36864
	ds_read_b128 v[174:177], v141 offset:37888
	ds_read_b128 v[178:181], v141 offset:38912
	ds_read_b128 v[182:185], v141 offset:39936
	global_load_lds_dwordx4 v[200:201], off
	v_lshl_add_u64 v[200:201], s[16:17], 0, v[128:129]
	s_mov_b32 m0, s21
	s_nop 0
	global_load_lds_dwordx4 v[200:201], off
	s_waitcnt lgkmcnt(8)
	s_barrier
	s_waitcnt lgkmcnt(0)
	s_setprio 1
	s_waitcnt lgkmcnt(0)
	v_mfma_f32_16x16x32_bf16 v[124:127], v[134:137], v[154:157], v[124:127]
	v_mfma_f32_16x16x32_bf16 v[120:123], v[146:149], v[154:157], v[120:123]
	v_mfma_f32_16x16x32_bf16 v[116:119], v[134:137], v[162:165], v[116:119]
	v_mfma_f32_16x16x32_bf16 v[112:115], v[146:149], v[162:165], v[112:115]
	v_mfma_f32_16x16x32_bf16 v[108:111], v[134:137], v[170:173], v[108:111]
	v_mfma_f32_16x16x32_bf16 v[100:103], v[146:149], v[170:173], v[100:103]
	v_mfma_f32_16x16x32_bf16 v[84:87], v[134:137], v[178:181], v[84:87]
	v_mfma_f32_16x16x32_bf16 v[72:75], v[146:149], v[178:181], v[72:75]
	v_mfma_f32_16x16x32_bf16 v[124:127], v[142:145], v[158:161], v[124:127]
	v_mfma_f32_16x16x32_bf16 v[120:123], v[150:153], v[158:161], v[120:123]
	v_mfma_f32_16x16x32_bf16 v[116:119], v[142:145], v[166:169], v[116:119]
	v_mfma_f32_16x16x32_bf16 v[112:115], v[150:153], v[166:169], v[112:115]
	v_mfma_f32_16x16x32_bf16 v[108:111], v[142:145], v[174:177], v[108:111]
	v_mfma_f32_16x16x32_bf16 v[100:103], v[150:153], v[174:177], v[100:103]
	v_mfma_f32_16x16x32_bf16 v[84:87], v[142:145], v[182:185], v[84:87]
	v_mfma_f32_16x16x32_bf16 v[72:75], v[150:153], v[182:185], v[72:75]
	s_setprio 0
	s_barrier
	s_add_i32 s16, s94, 0x100
	s_add_i32 s17, s28, s3
	v_add_u32_e32 v199, s16, v140
	v_lshl_add_u64 v[138:139], v[138:139], 0, s[96:97]
	s_mov_b32 m0, s17
	ds_read_b128 v[200:203], v199
	ds_read_b128 v[204:207], v199 offset:1024
	ds_read_b128 v[218:221], v199 offset:2048
	ds_read_b128 v[222:225], v199 offset:3072
	global_load_lds_dwordx4 v[138:139], off
	v_lshl_add_u64 v[138:139], v[186:187], 0, s[96:97]
	s_add_i32 m0, s17, 0x2000
	s_nop 0
	global_load_lds_dwordx4 v[138:139], off
	s_barrier
; #define G_STAGE(bufoff, gbase, v0, v1) do { \
;     __builtin_amdgcn_global_load_lds((const unsigned*)((const char*)(gbase) + (v0)), (LAS unsigned*)(lds + (bufoff) + ldsw), 16, 0, 0); \
;     __builtin_amdgcn_global_load_lds((const unsigned*)((const char*)(gbase) + (v1)), (LAS unsigned*)(lds + (bufoff) + ldsw + 8192), 16, 0, 0); } while (0)
; #define G_LDA(dst, b, h) do { _Pragma("unroll") for (int m = 0; m < 4; ++m) _Pragma("unroll") for (int k = 0; k < 2; ++k) dst[m][k] = *(const LAS bf16x8*)(lds + G_SA(b, h) + aoff + m * 2048 + k * 1024); } while (0)
; #define G_LDB(dst, b, h) do { _Pragma("unroll") for (int n = 0; n < 2; ++n) _Pragma("unroll") for (int k = 0; k < 2; ++k) dst[n][k] = *(const LAS bf16x8*)(lds + G_SB(b, h) + boff + n * 2048 + k * 1024); } while (0)
; #define G_MMA(ai, bj, At, Bt) do { __builtin_amdgcn_s_setprio(1); _Pragma("unroll") for (int m = 0; m < 4; ++m) _Pragma("unroll") for (int n = 0; n < 2; ++n) _Pragma("unroll") for (int k = 0; k < 2; ++k) \
;     acc[ai][bj][m][n] = __builtin_amdgcn_mfma_f32_16x16x32_bf16(Bt[n][k], At[m][k], acc[ai][bj][m][n], 0, 0, 0); __builtin_amdgcn_s_setprio(0); } while (0)
; #define G_WAIT_V(n) asm volatile("s_waitcnt vmcnt(" #n ")" ::: "memory")
; #define G_WAIT_L(n) asm volatile("s_waitcnt lgkmcnt(" #n ")" ::: "memory")
; #define G_BAR __builtin_amdgcn_s_barrier()
; #define G_SCHED __builtin_amdgcn_sched_barrier(0)
; __device__ __forceinline__ void gemm_run(const Params& p, int l, int kind, int single) {
;     ...
;       G_LDB(B1, 1, 1); G_STAGE(G_SB(1, 0), b3, w0, w1);
;       G_BAR; G_WAIT_L(0); G_MMA(0, 1, At, B1); G_BAR;
;       G_LDA(At, 1, 1); G_STAGE(G_SA(1, 0), a3, w0, w1);
;       G_BAR; G_WAIT_L(0); G_MMA(1, 0, At, B0); G_BAR; G_SCHED;
;       G_STAGE(G_SB(1, 1), b3 + h2, w0, w1);
;       G_WAIT_V(6); G_BAR; G_MMA(1, 1, At, B1); G_BAR;
;     }
;     ...
;   G_WAIT_V(0);
;   if (wr == 0) G_BAR;
	s_waitcnt lgkmcnt(0)
	s_setprio 1
	s_waitcnt lgkmcnt(0)
	v_mfma_f32_16x16x32_bf16 v[104:107], v[200:203], v[154:157], v[104:107]
	v_mfma_f32_16x16x32_bf16 v[96:99], v[218:221], v[154:157], v[96:99]
	v_mfma_f32_16x16x32_bf16 v[92:95], v[200:203], v[162:165], v[92:95]
	v_mfma_f32_16x16x32_bf16 v[88:91], v[218:221], v[162:165], v[88:91]
	v_mfma_f32_16x16x32_bf16 v[80:83], v[200:203], v[170:173], v[80:83]
	v_mfma_f32_16x16x32_bf16 v[76:79], v[218:221], v[170:173], v[76:79]
	v_mfma_f32_16x16x32_bf16 v[68:71], v[200:203], v[178:181], v[68:71]
	v_mfma_f32_16x16x32_bf16 v[64:67], v[218:221], v[178:181], v[64:67]
	v_mfma_f32_16x16x32_bf16 v[104:107], v[204:207], v[158:161], v[104:107]
	v_mfma_f32_16x16x32_bf16 v[96:99], v[222:225], v[158:161], v[96:99]
	v_mfma_f32_16x16x32_bf16 v[92:95], v[204:207], v[166:169], v[92:95]
	v_mfma_f32_16x16x32_bf16 v[88:91], v[222:225], v[166:169], v[88:91]
	v_mfma_f32_16x16x32_bf16 v[80:83], v[204:207], v[174:177], v[80:83]
	v_mfma_f32_16x16x32_bf16 v[76:79], v[222:225], v[174:177], v[76:79]
	v_mfma_f32_16x16x32_bf16 v[68:71], v[204:207], v[182:185], v[68:71]
	v_mfma_f32_16x16x32_bf16 v[64:67], v[222:225], v[182:185], v[64:67]
	s_setprio 0
	s_mov_b32 m0, s22
	v_lshl_add_u64 v[138:139], v[226:227], 0, s[96:97]
	s_barrier
	ds_read_b128 v[154:157], v141 offset:49152
	ds_read_b128 v[158:161], v141 offset:50176
	ds_read_b128 v[162:165], v141 offset:51200
	ds_read_b128 v[166:169], v141 offset:52224
	ds_read_b128 v[170:173], v141 offset:53248
	ds_read_b128 v[174:177], v141 offset:54272
	ds_read_b128 v[178:181], v141 offset:55296
	ds_read_b128 v[182:185], v141 offset:56320
	global_load_lds_dwordx4 v[138:139], off
	v_lshl_add_u64 v[138:139], v[228:229], 0, s[96:97]
	s_mov_b32 m0, s23
	s_nop 0
	global_load_lds_dwordx4 v[138:139], off
	s_barrier
	s_waitcnt lgkmcnt(0)
	s_setprio 1
	s_waitcnt lgkmcnt(0)
	v_mfma_f32_16x16x32_bf16 v[60:63], v[134:137], v[154:157], v[60:63]
	v_mfma_f32_16x16x32_bf16 v[56:59], v[146:149], v[154:157], v[56:59]
	v_mfma_f32_16x16x32_bf16 v[52:55], v[134:137], v[162:165], v[52:55]
	v_mfma_f32_16x16x32_bf16 v[48:51], v[146:149], v[162:165], v[48:51]
	v_mfma_f32_16x16x32_bf16 v[44:47], v[134:137], v[170:173], v[44:47]
	v_mfma_f32_16x16x32_bf16 v[36:39], v[146:149], v[170:173], v[36:39]
	v_mfma_f32_16x16x32_bf16 v[28:31], v[134:137], v[178:181], v[28:31]
	v_mfma_f32_16x16x32_bf16 v[16:19], v[146:149], v[178:181], v[16:19]
	v_mfma_f32_16x16x32_bf16 v[60:63], v[142:145], v[158:161], v[60:63]
	v_mfma_f32_16x16x32_bf16 v[56:59], v[150:153], v[158:161], v[56:59]
	v_mfma_f32_16x16x32_bf16 v[52:55], v[142:145], v[166:169], v[52:55]
	v_mfma_f32_16x16x32_bf16 v[48:51], v[150:153], v[166:169], v[48:51]
	v_mfma_f32_16x16x32_bf16 v[44:47], v[142:145], v[174:177], v[44:47]
	v_mfma_f32_16x16x32_bf16 v[36:39], v[150:153], v[174:177], v[36:39]
	v_mfma_f32_16x16x32_bf16 v[28:31], v[142:145], v[182:185], v[28:31]
	v_mfma_f32_16x16x32_bf16 v[16:19], v[150:153], v[182:185], v[16:19]
	s_setprio 0
	s_barrier
	s_add_u32 s14, s14, 0x40080
	s_addc_u32 s15, s15, 0
	s_add_i32 s16, s16, s3
	v_lshl_add_u64 v[134:135], s[14:15], 0, v[190:191]
	s_mov_b32 m0, s16
	s_nop 0
	global_load_lds_dwordx4 v[134:135], off
	v_lshl_add_u64 v[134:135], s[14:15], 0, v[128:129]
	s_add_i32 m0, s16, 0x2000
	s_nop 0
	global_load_lds_dwordx4 v[134:135], off
	s_waitcnt vmcnt(6)
	s_barrier
	s_setprio 1
	v_mfma_f32_16x16x32_bf16 v[40:43], v[200:203], v[154:157], v[40:43]
	v_mfma_f32_16x16x32_bf16 v[32:35], v[218:221], v[154:157], v[32:35]
	v_mfma_f32_16x16x32_bf16 v[24:27], v[200:203], v[162:165], v[24:27]
	v_mfma_f32_16x16x32_bf16 v[20:23], v[218:221], v[162:165], v[20:23]
	v_mfma_f32_16x16x32_bf16 v[12:15], v[200:203], v[170:173], v[12:15]
	v_mfma_f32_16x16x32_bf16 v[8:11], v[218:221], v[170:173], v[8:11]
	v_mfma_f32_16x16x32_bf16 v[4:7], v[200:203], v[178:181], v[4:7]
	v_mfma_f32_16x16x32_bf16 v[0:3], v[218:221], v[178:181], v[0:3]
	v_mfma_f32_16x16x32_bf16 v[40:43], v[204:207], v[158:161], v[40:43]
	v_mfma_f32_16x16x32_bf16 v[32:35], v[222:225], v[158:161], v[32:35]
	v_mfma_f32_16x16x32_bf16 v[24:27], v[204:207], v[166:169], v[24:27]
	v_mfma_f32_16x16x32_bf16 v[20:23], v[222:225], v[166:169], v[20:23]
	v_mfma_f32_16x16x32_bf16 v[12:15], v[204:207], v[174:177], v[12:15]
	v_mfma_f32_16x16x32_bf16 v[8:11], v[222:225], v[174:177], v[8:11]
	v_mfma_f32_16x16x32_bf16 v[4:7], v[204:207], v[182:185], v[4:7]
	v_mfma_f32_16x16x32_bf16 v[0:3], v[222:225], v[182:185], v[0:3]
	s_setprio 0
	s_add_i32 s27, s27, 2
	s_add_u32 s12, s12, 0x100
	s_addc_u32 s13, s13, 0
	s_add_u32 s1, s1, 0x100
	s_addc_u32 s5, s5, 0
	s_cmp_gt_u32 s27, 13
	s_barrier
	s_cbranch_scc0 .LBB0_1012
	s_cmpk_gt_u32 s2, 0xff
	s_cbranch_scc1 .Lal4_a
	s_barrier
; __device__ __forceinline__ int otid() { int t = threadIdx.x; asm volatile("" : "+v"(t)); return t; }
; __device__ __forceinline__ void gemm_epi(const Params& p, int l, int kind, const GUnit& u, f32x4 (&acc)[2][2][4][2]) {
;   const int tid = otid(), wid = __builtin_amdgcn_readfirstlane(tid >> 6), lane = tid & 63, wr = wid >> 2, wc = wid & 3, fr = lane & 15, fq = lane >> 4;
;   int row0 = u.pm * 256 + wr * 64 + fr;
;   asm volatile("" : "+v"(row0));
;   if (kind == 4) {
;     const int col0 = u.pn * 256 + wc * 32 + 4 * fq;
;     const float* xbase = (l == 0) ? (u.pm < 256 ? p.xp : p.xs - (long)NP * 1024) : p.out;
; #pragma unroll
;     for (int ai = 0; ai < 2; ++ai) {
;       f32x4 xv[4][2][2];
; #pragma unroll
;       for (int m = 0; m < 4; ++m) {
;         const float* xr = xbase + (long)(row0 + ai * 128 + m * 16) * 1024 + col0;
; #pragma unroll
;         for (int bj = 0; bj < 2; ++bj)
; #pragma unroll
;           for (int n = 0; n < 2; ++n) xv[m][bj][n] = *reinterpret_cast<const f32x4*>(xr + bj * 128 + n * 16);
;       }
.Lal4_a:
	v_mov_b32_e32 v134, v188
	s_lshl_b32 s5, s25, 8
	v_readfirstlane_b32 s1, v134
	s_ashr_i32 s12, s1, 2
	s_andn2_b32 s12, s12, 63
	s_lshr_b32 s1, s1, 1
	s_add_i32 s12, s12, s5
	s_lshl_b32 s5, s26, 8
	s_and_b32 s1, s1, 0x60
	s_or_b32 s1, s1, s5
	v_readlane_b32 s36, v248, 20
	v_and_or_b32 v138, v134, 15, s12
	v_lshrrev_b32_e32 v134, 2, v134
	s_cmpk_lt_i32 s25, 0x100
	v_readlane_b32 s37, v248, 21
	v_readlane_b32 s38, v248, 22
	v_readlane_b32 s39, v248, 23
	v_readlane_b32 s40, v248, 24
	v_readlane_b32 s41, v248, 25
	v_readlane_b32 s42, v248, 26
	v_readlane_b32 s43, v248, 27
	v_readlane_b32 s12, v247, 48
	v_and_or_b32 v134, v134, 12, s1
	s_cselect_b32 s1, s36, s81
	s_cselect_b32 s5, s37, s88
	v_readlane_b32 s13, v247, 49
	v_readlane_b32 s36, v248, 49
	s_and_b64 s[12:13], s[12:13], exec
	v_readlane_b32 s37, v248, 50
	v_ashrrev_i32_e32 v135, 31, v134
	s_cselect_b32 s13, s5, s37
	s_cselect_b32 s12, s1, s36
	v_lshlrev_b64 v[134:135], 2, v[134:135]
	v_ashrrev_i32_e32 v139, 31, v138
	v_lshl_add_u64 v[136:137], s[12:13], 0, v[134:135]
	v_lshlrev_b64 v[138:139], 12, v[138:139]
	s_mov_b64 s[12:13], 0x10000
	v_lshl_add_u64 v[186:187], v[138:139], 0, s[12:13]
	s_mov_b64 s[12:13], 0x20000
	v_lshl_add_u64 v[230:231], v[138:139], 0, s[12:13]
	s_mov_b64 s[12:13], 0x30000
	v_lshl_add_u64 v[154:155], v[136:137], 0, v[138:139]
	v_lshl_add_u64 v[232:233], v[138:139], 0, s[12:13]
	global_load_dwordx4 v[142:145], v[154:155], off
	global_load_dwordx4 v[146:149], v[154:155], off offset:64
	global_load_dwordx4 v[150:153], v[154:155], off offset:512
	s_nop 0
	global_load_dwordx4 v[154:157], v[154:155], off offset:576
	v_lshl_add_u64 v[170:171], v[136:137], 0, v[186:187]
	v_lshl_add_u64 v[200:201], v[136:137], 0, v[230:231]
	v_lshl_add_u64 v[226:227], v[136:137], 0, v[232:233]
	global_load_dwordx4 v[158:161], v[170:171], off
	global_load_dwordx4 v[162:165], v[170:171], off offset:64
	global_load_dwordx4 v[166:169], v[170:171], off offset:512
	s_nop 0
	global_load_dwordx4 v[170:173], v[170:171], off offset:576
	s_nop 0
	global_load_dwordx4 v[174:177], v[200:201], off
	global_load_dwordx4 v[178:181], v[200:201], off offset:64
	global_load_dwordx4 v[182:185], v[200:201], off offset:512
	s_nop 0
	global_load_dwordx4 v[200:203], v[200:201], off offset:576
	s_nop 0
	global_load_dwordx4 v[204:207], v[226:227], off
	global_load_dwordx4 v[218:221], v[226:227], off offset:64
	global_load_dwordx4 v[222:225], v[226:227], off offset:512
	s_nop 0
	global_load_dwordx4 v[226:229], v[226:227], off offset:576
	v_lshl_add_u64 v[234:235], s[36:37], 0, v[138:139]
	v_lshl_add_u64 v[234:235], v[234:235], 0, v[134:135]
	v_lshl_add_u64 v[186:187], s[36:37], 0, v[186:187]
	v_lshl_add_u64 v[232:233], s[36:37], 0, v[232:233]
	v_lshl_add_u64 v[230:231], s[36:37], 0, v[230:231]
	v_lshl_add_u64 v[186:187], v[186:187], 0, v[134:135]
	v_lshl_add_u64 v[232:233], v[232:233], 0, v[134:135]
	v_readlane_b32 s38, v248, 51
	v_readlane_b32 s39, v248, 52
	v_readlane_b32 s40, v248, 53
	v_readlane_b32 s41, v248, 54
	v_readlane_b32 s42, v248, 55
	v_readlane_b32 s43, v248, 56
	v_readlane_b32 s44, v248, 57
	v_readlane_b32 s45, v248, 58
	v_readlane_b32 s46, v248, 59
	v_readlane_b32 s47, v248, 60
	v_readlane_b32 s48, v248, 61
	v_readlane_b32 s49, v248, 62
	v_readlane_b32 s50, v248, 63
	v_readlane_b32 s51, v247, 0
	v_lshl_add_u64 v[230:231], v[230:231], 0, v[134:135]
	s_waitcnt vmcnt(0)
; #define G_WAIT_V(n) asm volatile("s_waitcnt vmcnt(" #n ")" ::: "memory")
; #define G_BAR __builtin_amdgcn_s_barrier()
; __device__ __forceinline__ void gemm_epi(const Params& p, int l, int kind, const GUnit& u, f32x4 (&acc)[2][2][4][2]) {
;     ...
;     for (int ai = 0; ai < 2; ++ai) {
;       f32x4 xv[4][2][2];
; #pragma unroll
;       for (int m = 0; m < 4; ++m) {
;         const float* xr = xbase + (long)(row0 + ai * 128 + m * 16) * 1024 + col0;
; #pragma unroll
;         for (int bj = 0; bj < 2; ++bj)
; #pragma unroll
;           for (int n = 0; n < 2; ++n) xv[m][bj][n] = *reinterpret_cast<const f32x4*>(xr + bj * 128 + n * 16);
;       }
; #pragma unroll
;       for (int m = 0; m < 4; ++m) {
;         float* yr = p.out + (long)(row0 + ai * 128 + m * 16) * 1024 + col0;
; #pragma unroll
;         for (int bj = 0; bj < 2; ++bj)
; #pragma unroll
;           for (int n = 0; n < 2; ++n) *reinterpret_cast<f32x4*>(yr + bj * 128 + n * 16) = xv[m][bj][n] + acc[ai][bj][m][n];
;       }
;       __builtin_amdgcn_sched_barrier(0);
;     }
; __device__ __forceinline__ void gemm_run(const Params& p, int l, int kind, int single) {
;     ...
;     gemm_epi(p, l, kind, cur, acc);
;     if (!has_next) break;
; #pragma unroll
;     for (int a = 0; a < 2; ++a)
; #pragma unroll
;       for (int b = 0; b < 2; ++b)
; #pragma unroll
;         for (int m = 0; m < 4; ++m)
; #pragma unroll
;           for (int n = 0; n < 2; ++n) acc[a][b][m][n] = f32x4{0.f, 0.f, 0.f, 0.f};
;     cur = nxt; cA = nA; cB = nB; vc0 = vn0; vc1 = vn1; hc = hn; ++ui;
;   }
;   G_WAIT_V(0);
;   if (wr == 0) G_BAR;
	v_pk_add_f32 v[126:127], v[126:127], v[144:145]
	v_pk_add_f32 v[124:125], v[124:125], v[142:143]
	v_pk_add_f32 v[122:123], v[122:123], v[148:149]
	v_pk_add_f32 v[98:99], v[98:99], v[156:157]
	v_pk_add_f32 v[96:97], v[96:97], v[154:155]
	v_pk_add_f32 v[120:121], v[120:121], v[146:147]
	v_pk_add_f32 v[106:107], v[106:107], v[152:153]
	v_pk_add_f32 v[104:105], v[104:105], v[150:151]
	global_store_dwordx4 v[234:235], v[124:127], off
	global_store_dwordx4 v[234:235], v[120:123], off offset:64
	global_store_dwordx4 v[234:235], v[104:107], off offset:512
	global_store_dwordx4 v[234:235], v[96:99], off offset:576
	v_pk_add_f32 v[86:87], v[86:87], v[206:207]
	v_pk_add_f32 v[84:85], v[84:85], v[204:205]
	v_pk_add_f32 v[98:99], v[118:119], v[160:161]
	v_pk_add_f32 v[96:97], v[116:117], v[158:159]
	v_pk_add_f32 v[74:75], v[74:75], v[220:221]
	v_pk_add_f32 v[72:73], v[72:73], v[218:219]
	v_pk_add_f32 v[70:71], v[70:71], v[224:225]
	v_pk_add_f32 v[68:69], v[68:69], v[222:223]
	v_pk_add_f32 v[66:67], v[66:67], v[228:229]
	v_pk_add_f32 v[64:65], v[64:65], v[226:227]
	v_pk_add_f32 v[106:107], v[114:115], v[164:165]
	v_pk_add_f32 v[104:105], v[112:113], v[162:163]
	v_pk_add_f32 v[94:95], v[94:95], v[168:169]
	v_pk_add_f32 v[92:93], v[92:93], v[166:167]
	v_pk_add_f32 v[90:91], v[90:91], v[172:173]
	v_pk_add_f32 v[88:89], v[88:89], v[170:171]
	v_pk_add_f32 v[110:111], v[110:111], v[176:177]
	v_pk_add_f32 v[108:109], v[108:109], v[174:175]
	v_pk_add_f32 v[102:103], v[102:103], v[180:181]
	v_pk_add_f32 v[100:101], v[100:101], v[178:179]
	v_pk_add_f32 v[82:83], v[82:83], v[184:185]
	v_pk_add_f32 v[80:81], v[80:81], v[182:183]
	v_pk_add_f32 v[78:79], v[78:79], v[202:203]
	v_pk_add_f32 v[76:77], v[76:77], v[200:201]
	global_store_dwordx4 v[186:187], v[96:99], off
	global_store_dwordx4 v[186:187], v[104:107], off offset:64
	global_store_dwordx4 v[186:187], v[92:95], off offset:512
	global_store_dwordx4 v[186:187], v[88:91], off offset:576
	global_store_dwordx4 v[230:231], v[108:111], off
	global_store_dwordx4 v[230:231], v[100:103], off offset:64
	global_store_dwordx4 v[230:231], v[80:83], off offset:512
	global_store_dwordx4 v[230:231], v[76:79], off offset:576
	global_store_dwordx4 v[232:233], v[84:87], off
	global_store_dwordx4 v[232:233], v[72:75], off offset:64
	global_store_dwordx4 v[232:233], v[68:71], off offset:512
	global_store_dwordx4 v[232:233], v[64:67], off offset:576
	s_mov_b64 s[12:13], 0x80000
	v_lshl_add_u64 v[142:143], v[138:139], 0, s[12:13]
	s_mov_b64 s[12:13], 0x90000
	v_lshl_add_u64 v[144:145], v[138:139], 0, s[12:13]
	s_mov_b64 s[12:13], 0xa0000
	v_lshl_add_u64 v[146:147], v[138:139], 0, s[12:13]
	s_mov_b64 s[12:13], 0xb0000
	v_lshl_add_u64 v[138:139], v[138:139], 0, s[12:13]
	v_lshl_add_u64 v[76:77], v[136:137], 0, v[142:143]
	v_lshl_add_u64 v[92:93], v[136:137], 0, v[144:145]
	v_lshl_add_u64 v[108:109], v[136:137], 0, v[146:147]
	v_lshl_add_u64 v[124:125], v[136:137], 0, v[138:139]
	global_load_dwordx4 v[64:67], v[76:77], off
	global_load_dwordx4 v[68:71], v[76:77], off offset:64
	global_load_dwordx4 v[72:75], v[76:77], off offset:512
	v_lshl_add_u64 v[136:137], s[36:37], 0, v[142:143]
	global_load_dwordx4 v[76:79], v[76:77], off offset:576
	s_nop 0
	global_load_dwordx4 v[80:83], v[92:93], off
	global_load_dwordx4 v[84:87], v[92:93], off offset:64
	global_load_dwordx4 v[88:91], v[92:93], off offset:512
	v_lshl_add_u64 v[142:143], s[36:37], 0, v[144:145]
	global_load_dwordx4 v[92:95], v[92:93], off offset:576
	s_nop 0
	global_load_dwordx4 v[96:99], v[108:109], off
	global_load_dwordx4 v[100:103], v[108:109], off offset:64
	global_load_dwordx4 v[104:107], v[108:109], off offset:512
	v_lshl_add_u64 v[144:145], s[36:37], 0, v[146:147]
	global_load_dwordx4 v[108:111], v[108:109], off offset:576
	s_nop 0
	global_load_dwordx4 v[112:115], v[124:125], off
	global_load_dwordx4 v[116:119], v[124:125], off offset:64
	global_load_dwordx4 v[120:123], v[124:125], off offset:512
	s_nop 0
	global_load_dwordx4 v[124:127], v[124:125], off offset:576
	v_lshl_add_u64 v[138:139], s[36:37], 0, v[138:139]
	v_lshl_add_u64 v[136:137], v[136:137], 0, v[134:135]
	v_lshl_add_u64 v[142:143], v[142:143], 0, v[134:135]
	v_lshl_add_u64 v[144:145], v[144:145], 0, v[134:135]
	v_lshl_add_u64 v[134:135], v[138:139], 0, v[134:135]
	s_waitcnt vmcnt(0)
	v_pk_add_f32 v[62:63], v[62:63], v[66:67]
	v_pk_add_f32 v[60:61], v[60:61], v[64:65]
	v_pk_add_f32 v[58:59], v[58:59], v[70:71]
	v_pk_add_f32 v[56:57], v[56:57], v[68:69]
	v_pk_add_f32 v[42:43], v[42:43], v[74:75]
	v_pk_add_f32 v[40:41], v[40:41], v[72:73]
	v_pk_add_f32 v[34:35], v[34:35], v[78:79]
	v_pk_add_f32 v[32:33], v[32:33], v[76:77]
	v_pk_add_f32 v[54:55], v[54:55], v[82:83]
	v_pk_add_f32 v[52:53], v[52:53], v[80:81]
	v_pk_add_f32 v[50:51], v[50:51], v[86:87]
	v_pk_add_f32 v[48:49], v[48:49], v[84:85]
	v_pk_add_f32 v[26:27], v[26:27], v[90:91]
	v_pk_add_f32 v[24:25], v[24:25], v[88:89]
	v_pk_add_f32 v[22:23], v[22:23], v[94:95]
	v_pk_add_f32 v[20:21], v[20:21], v[92:93]
	v_pk_add_f32 v[46:47], v[46:47], v[98:99]
	v_pk_add_f32 v[44:45], v[44:45], v[96:97]
	v_pk_add_f32 v[38:39], v[38:39], v[102:103]
	v_pk_add_f32 v[36:37], v[36:37], v[100:101]
	v_pk_add_f32 v[14:15], v[14:15], v[106:107]
	v_pk_add_f32 v[12:13], v[12:13], v[104:105]
	v_pk_add_f32 v[10:11], v[10:11], v[110:111]
	v_pk_add_f32 v[8:9], v[8:9], v[108:109]
	v_pk_add_f32 v[30:31], v[30:31], v[114:115]
	v_pk_add_f32 v[28:29], v[28:29], v[112:113]
	v_pk_add_f32 v[18:19], v[18:19], v[118:119]
	v_pk_add_f32 v[16:17], v[16:17], v[116:117]
	v_pk_add_f32 v[6:7], v[6:7], v[122:123]
	v_pk_add_f32 v[4:5], v[4:5], v[120:121]
	v_pk_add_f32 v[2:3], v[2:3], v[126:127]
	v_pk_add_f32 v[0:1], v[0:1], v[124:125]
	global_store_dwordx4 v[136:137], v[60:63], off
	global_store_dwordx4 v[136:137], v[56:59], off offset:64
	global_store_dwordx4 v[136:137], v[40:43], off offset:512
	global_store_dwordx4 v[136:137], v[32:35], off offset:576
	global_store_dwordx4 v[142:143], v[52:55], off
	global_store_dwordx4 v[142:143], v[48:51], off offset:64
	global_store_dwordx4 v[142:143], v[24:27], off offset:512
	global_store_dwordx4 v[142:143], v[20:23], off offset:576
	global_store_dwordx4 v[144:145], v[44:47], off
	global_store_dwordx4 v[144:145], v[36:39], off offset:64
	global_store_dwordx4 v[144:145], v[12:15], off offset:512
	global_store_dwordx4 v[144:145], v[8:11], off offset:576
	global_store_dwordx4 v[134:135], v[28:31], off
	global_store_dwordx4 v[134:135], v[16:19], off offset:64
	global_store_dwordx4 v[134:135], v[4:7], off offset:512
	global_store_dwordx4 v[134:135], v[0:3], off offset:576
	s_and_b64 vcc, exec, s[6:7]
	s_mov_b32 s25, s4
	s_mov_b32 s26, s0
	s_mov_b64 s[14:15], s[10:11]
	s_mov_b64 s[12:13], s[8:9]
	s_cbranch_vccnz .Lal4_exit
	s_cmpk_gt_u32 s2, 0xff
	s_cbranch_scc0 .LBB0_1009
	s_barrier
	s_branch .LBB0_1009
.Lal4_exit:
	s_waitcnt vmcnt(0)
	v_readlane_b32 s22, v248, 42

; __global__ void __launch_bounds__(NTHR) fwd_mega(Params p, int ph_lo, int ph_hi) {
	.amdhsa_kernel _Z8fwd_mega6Paramsii
		.amdhsa_group_segment_fixed_size 256
		.amdhsa_private_segment_fixed_size 0
		.amdhsa_kernarg_size 536
		.amdhsa_user_sgpr_count 2
		.amdhsa_user_sgpr_dispatch_ptr 0
		.amdhsa_user_sgpr_queue_ptr 0
		.amdhsa_user_sgpr_kernarg_segment_ptr 1
		.amdhsa_user_sgpr_dispatch_id 0
		.amdhsa_user_sgpr_kernarg_preload_length 0
		.amdhsa_user_sgpr_kernarg_preload_offset 0
		.amdhsa_user_sgpr_private_segment_size 0
		.amdhsa_uses_dynamic_stack 0
		.amdhsa_enable_private_segment 0
		.amdhsa_system_sgpr_workgroup_id_x 1
		.amdhsa_system_sgpr_workgroup_id_y 0
		.amdhsa_system_sgpr_workgroup_id_z 0
		.amdhsa_system_sgpr_workgroup_info 0
		.amdhsa_system_vgpr_workitem_id 2
		.amdhsa_next_free_vgpr 252
		.amdhsa_next_free_sgpr 98
		.amdhsa_accum_offset 252
		.amdhsa_reserve_vcc 1
		.amdhsa_float_round_mode_32 0
		.amdhsa_float_round_mode_16_64 0
		.amdhsa_float_denorm_mode_32 3
		.amdhsa_float_denorm_mode_16_64 3
		.amdhsa_dx10_clamp 1
		.amdhsa_ieee_mode 1
		.amdhsa_fp16_overflow 0
		.amdhsa_tg_split 0
		.amdhsa_exception_fp_ieee_invalid_op 0
		.amdhsa_exception_fp_denorm_src 0
		.amdhsa_exception_fp_ieee_div_zero 0
		.amdhsa_exception_fp_ieee_overflow 0
		.amdhsa_exception_fp_ieee_underflow 0
		.amdhsa_exception_fp_ieee_inexact 0
		.amdhsa_exception_int_div_zero 0
	.end_amdhsa_kernel

; __global__ void __launch_bounds__(NTHR) fwd_mega(Params p, int ph_lo, int ph_hi) {
amdhsa.kernels:
  - .agpr_count:     0
    .args:
      - .offset:         0
        .size:           272
        .value_kind:     by_value
      - .offset:         272
        .size:           4
        .value_kind:     by_value
      - .offset:         276
        .size:           4
        .value_kind:     by_value
      - .offset:         280
        .size:           4
        .value_kind:     hidden_block_count_x
      - .offset:         284
        .size:           4
        .value_kind:     hidden_block_count_y
      - .offset:         288
        .size:           4
        .value_kind:     hidden_block_count_z
      - .offset:         292
        .size:           2
        .value_kind:     hidden_group_size_x
      - .offset:         294
        .size:           2
        .value_kind:     hidden_group_size_y
      - .offset:         296
        .size:           2
        .value_kind:     hidden_group_size_z
      - .offset:         298
        .size:           2
        .value_kind:     hidden_remainder_x
      - .offset:         300
        .size:           2
        .value_kind:     hidden_remainder_y
      - .offset:         302
        .size:           2
        .value_kind:     hidden_remainder_z
      - .offset:         320
        .size:           8
        .value_kind:     hidden_global_offset_x
      - .offset:         328
        .size:           8
        .value_kind:     hidden_global_offset_y
      - .offset:         336
        .size:           8
        .value_kind:     hidden_global_offset_z
      - .offset:         344
        .size:           2
        .value_kind:     hidden_grid_dims
      - .offset:         368
        .size:           8
        .value_kind:     hidden_multigrid_sync_arg
      - .offset:         400
        .size:           4
        .value_kind:     hidden_dynamic_lds_size
    .group_segment_fixed_size: 256
    .kernarg_segment_align: 8
    .kernarg_segment_size: 536
    .language:       OpenCL C
    .language_version:
      - 2
      - 0
    .max_flat_workgroup_size: 512
    .name:           _Z8fwd_mega6Paramsii
    .private_segment_fixed_size: 0
    .sgpr_count:     104
    .sgpr_spill_count: 181
    .symbol:         _Z8fwd_mega6Paramsii.kd
    .uniform_work_group_size: 1
    .uses_dynamic_stack: false
    .vgpr_count:     252
    .vgpr_spill_count: 0
    .wavefront_size: 64
